# residual phases: meta-row split-K partial sums spread over wave 0 of 16 workgroups (was 16 waves on 2 CUs, per-CU bandwidth bound); 24 loads deep
# speedup vs baseline: 1.0230x; 1.0219x over previous
; __device__ __forceinline__ int opaque_tid() { int t = threadIdx.x; asm volatile("" : "+v"(t)); return t; }
; __device__ __forceinline__ void phase_resid(const Params& p, const float* g, bool first, bool last, int nsplit) {
;     const int tid = opaque_tid(), lane = tid & 63, gw = (blockIdx.x * NTHREADS + tid) >> 6, nw = (gridDim.x * NTHREADS) >> 6;
;     float* h = (float*)(p.ws + WS_H); bf16_t* abf = (bf16_t*)(p.ws + WS_ABF);
;     const bf16_t* mix = (const bf16_t*)(p.ws + WS_MIX);
;     const float* part = (const float*)(p.ws + WS_PART);
;     f32x4 gv[8];
; #pragma unroll
;     for (int i = 0; i < 8; ++i) gv[i] = *(const f32x4*)(g + lane * 4 + 256 * i);
;     ...
;     if (gw < 16) {
;         const int row = PADR + gw;
;         f32x4 mv[8], hv[8];
; #pragma unroll
;         for (int i = 0; i < 8; ++i) { mv[i] = (f32x4){0.f, 0.f, 0.f, 0.f}; hv[i] = *(const f32x4*)(HROW(row) + lane * 4 + 256 * i); }
;         for (int sp = 0; sp < nsplit; ++sp) {
; #pragma unroll
;             for (int i = 0; i < 8; ++i) mv[i] += *(const f32x4*)(part + (size_t)(sp * 16 + gw) * DM + lane * 4 + 256 * i);
;         }
.LBB0_300:
	v_writelane_b32 v254, s49, 28
	v_writelane_b32 v254, s48, 29
	v_writelane_b32 v254, s45, 30
	v_writelane_b32 v254, s44, 31
	v_writelane_b32 v254, s43, 32
	v_writelane_b32 v254, s42, 33
	v_writelane_b32 v254, s37, 34
	v_writelane_b32 v254, s36, 35
	v_writelane_b32 v254, s33, 36
	v_writelane_b32 v254, s29, 37
	v_writelane_b32 v254, s22, 38
	s_ashr_i32 s91, s90, 31
	s_nop 0
	v_writelane_b32 v254, s23, 39
	v_writelane_b32 v254, s21, 40
	v_writelane_b32 v254, s20, 41
	v_writelane_b32 v254, s19, 42
	v_writelane_b32 v254, s18, 43
	v_writelane_b32 v254, s17, 44
	v_writelane_b32 v254, s16, 45
	v_writelane_b32 v254, s12, 46
	v_writelane_b32 v254, s11, 47
	v_writelane_b32 v254, s10, 48
	v_writelane_b32 v254, s9, 49
	v_writelane_b32 v254, s8, 50
	v_writelane_b32 v254, s7, 51
	v_writelane_b32 v254, s5, 52
	s_mul_i32 s5, s90, 0x6280000
	v_writelane_b32 v254, s4, 53
	s_mul_hi_i32 s4, s90, 0x6280000
	s_add_u32 s5, s34, s5
	v_writelane_b32 v254, s5, 54
	s_addc_u32 s4, s35, s4
	v_writelane_b32 v254, s4, 55
	v_writelane_b32 v254, s50, 56
	s_cmp_lt_i32 s50, 5
	s_mov_b64 s[4:5], -1
	v_writelane_b32 v254, s31, 57
	s_cbranch_scc1 .LBB0_763
	v_readlane_b32 s4, v254, 56
	s_cmp_lt_i32 s4, 7
	s_mov_b64 s[4:5], -1
	s_cbranch_scc1 .LBB0_382
	v_readlane_b32 s4, v254, 56
	s_cmp_gt_i32 s4, 7
	s_mov_b64 s[4:5], -1
	s_cbranch_scc0 .LBB0_350
	s_lshl_b32 s4, s90, 11
	s_ashr_i32 s5, s4, 31
	v_mov_b32_e32 v34, v210
	s_lshl_b64 s[4:5], s[4:5], 2
	s_add_u32 s4, s6, s4
	v_lshlrev_b32_e32 v0, 2, v34
	v_and_b32_e32 v116, 0xfc, v0
	s_addc_u32 s5, s3, s5
	v_lshlrev_b32_e32 v0, 2, v116
	v_lshl_add_u64 v[18:19], s[4:5], 0, v[0:1]
	v_add_co_u32_e32 v30, vcc, 0x1000, v18
	global_load_dwordx4 v[2:5], v0, s[4:5]
	global_load_dwordx4 v[6:9], v0, s[4:5] offset:1024
	global_load_dwordx4 v[10:13], v0, s[4:5] offset:2048
	global_load_dwordx4 v[14:17], v0, s[4:5] offset:3072
	v_addc_co_u32_e32 v31, vcc, 0, v19, vcc
	global_load_dwordx4 v[18:21], v[30:31], off
	global_load_dwordx4 v[22:25], v[30:31], off offset:1024
	global_load_dwordx4 v[26:29], v[30:31], off offset:2048
	s_nop 0
	global_load_dwordx4 v[30:33], v[30:31], off offset:3072
	s_sub_i32 s3, s31, 28
	s_cmp_lt_u32 s3, 9
	s_cselect_b64 s[4:5], -1, 0
	s_cmp_gt_u32 s3, 8
	v_readlane_b32 s3, v252, 5
	s_cselect_b64 s[8:9], -1, 0
	s_add_u32 s16, s34, 0x18a00000
	v_add_u32_e32 v35, s3, v34
	s_movk_i32 s3, 0x400
	s_addc_u32 s17, s35, 0
	v_lshrrev_b32_e32 v70, 6, v35
	v_cmp_gt_u32_e32 vcc, 64, v34
	s_cmp_lt_u32 s80, 16
	s_cselect_b64 s[100:101], -1, 0
	s_and_b64 vcc, vcc, s[100:101]
	v_mov_b32_e32 v250, s80
	v_mov_b32_e32 v251, 0
	v_and_b32_e32 v148, 63, v34
	s_and_saveexec_b64 s[10:11], vcc
	v_readlane_b32 s12, v254, 5
	s_mov_b32 s3, 0x415c8000
	s_mov_b32 s20, 0x415c9000
	s_mov_b32 s21, 0x415ca000
	s_mov_b32 s22, 0x415e8000
	s_mov_b32 s23, 0x415e9000
	s_mov_b32 s25, 0x415ea000
	s_cbranch_execz .LBB0_308
	v_mov_b32_e32 v34, 0x78000
	v_lshl_or_b32 v66, v250, 11, v34
	v_mov_b32_e32 v67, v1
	v_lshl_add_u64 v[34:35], v[66:67], 2, s[16:17]
	v_lshl_add_u64 v[68:69], v[34:35], 0, v[0:1]
	v_add_co_u32_e32 v34, vcc, 0x1000, v68
	global_load_dwordx4 v[62:65], v[68:69], off
	global_load_dwordx4 v[58:61], v[68:69], off offset:1024
	global_load_dwordx4 v[54:57], v[68:69], off offset:2048
	global_load_dwordx4 v[50:53], v[68:69], off offset:3072
	v_addc_co_u32_e32 v35, vcc, 0, v69, vcc
	global_load_dwordx4 v[46:49], v[34:35], off
	global_load_dwordx4 v[42:45], v[34:35], off offset:1024
	global_load_dwordx4 v[38:41], v[34:35], off offset:2048
	s_nop 0
	global_load_dwordx4 v[34:37], v[34:35], off offset:3072
	s_mov_b64 s[6:7], 0x1000
	v_lshl_add_u64 v[78:79], v[68:69], 0, s[6:7]
	s_mov_b64 s[6:7], 0x1400
	v_mov_b32_e32 v71, v1
	v_lshl_add_u64 v[72:73], v[68:69], 0, s[6:7]
	s_mov_b64 s[6:7], 0x1800
	v_lshlrev_b64 v[80:81], 13, v[250:251]
	v_lshl_add_u64 v[74:75], v[68:69], 0, s[6:7]
	s_mov_b64 s[6:7], 0x1c00
	v_lshl_or_b32 v80, v148, 4, v80
	v_mov_b32_e32 v88, 0
	v_lshl_add_u64 v[76:77], v[68:69], 0, s[6:7]
	v_lshl_add_u64 v[96:97], s[34:35], 0, v[80:81]
	s_mov_b64 s[18:19], 0
	v_mov_b32_e32 v89, v88
	v_mov_b32_e32 v90, v88
	v_mov_b32_e32 v91, v88
	v_mov_b32_e32 v80, v88
	v_mov_b32_e32 v81, v88
	v_mov_b32_e32 v82, v88
	v_mov_b32_e32 v83, v88
	v_mov_b32_e32 v84, v88
	v_mov_b32_e32 v85, v88
	v_mov_b32_e32 v86, v88
	v_mov_b32_e32 v87, v88
	v_mov_b32_e32 v92, v88
	v_mov_b32_e32 v93, v88
	v_mov_b32_e32 v94, v88
	v_mov_b32_e32 v95, v88
	v_mov_b32_e32 v98, v88
	v_mov_b32_e32 v99, v88
	v_mov_b32_e32 v100, v88
	v_mov_b32_e32 v101, v88
	v_mov_b32_e32 v102, v88
	v_mov_b32_e32 v103, v88
	v_mov_b32_e32 v104, v88
	v_mov_b32_e32 v105, v88
	v_mov_b32_e32 v106, v88
	v_mov_b32_e32 v107, v88
	v_mov_b32_e32 v108, v88
	v_mov_b32_e32 v109, v88
	v_mov_b32_e32 v110, v88
	v_mov_b32_e32 v111, v88
	v_mov_b32_e32 v112, v88
	v_mov_b32_e32 v113, v88
	v_subrev_u32_e32 v117, s34, v96
	v_add_u32_e32 v118, 0x1000, v117
	v_add_u32_e32 v119, 0x2000, v117
	s_add_u32 s100, s34, 0x415c8000
	s_addc_u32 s101, s35, 0
	global_load_dwordx4 v[120:123], v117, s[100:101] offset:1280
	global_load_dwordx4 v[124:127], v117, s[100:101] offset:2304
	global_load_dwordx4 v[128:131], v117, s[100:101] offset:3328
	global_load_dwordx4 v[132:135], v118, s[100:101] offset:256
	global_load_dwordx4 v[136:139], v118, s[100:101] offset:1280
	global_load_dwordx4 v[140:143], v118, s[100:101] offset:2304
	global_load_dwordx4 v[144:147], v118, s[100:101] offset:3328
	global_load_dwordx4 v[152:155], v119, s[100:101] offset:256
	s_add_u32 s100, s100, 0x20000
	s_addc_u32 s101, s101, 0
	global_load_dwordx4 v[156:159], v117, s[100:101] offset:1280
	global_load_dwordx4 v[160:163], v117, s[100:101] offset:2304
	global_load_dwordx4 v[164:167], v117, s[100:101] offset:3328
	global_load_dwordx4 v[168:171], v118, s[100:101] offset:256
	global_load_dwordx4 v[172:175], v118, s[100:101] offset:1280
	global_load_dwordx4 v[176:179], v118, s[100:101] offset:2304
	global_load_dwordx4 v[180:183], v118, s[100:101] offset:3328
	global_load_dwordx4 v[184:187], v119, s[100:101] offset:256
	s_add_u32 s100, s100, 0x20000
	s_addc_u32 s101, s101, 0
	global_load_dwordx4 v[188:191], v117, s[100:101] offset:1280
	global_load_dwordx4 v[192:195], v117, s[100:101] offset:2304
	global_load_dwordx4 v[196:199], v117, s[100:101] offset:3328
	global_load_dwordx4 v[200:203], v118, s[100:101] offset:256
	global_load_dwordx4 v[204:207], v118, s[100:101] offset:1280
	global_load_dwordx4 v[224:227], v118, s[100:101] offset:2304
	global_load_dwordx4 v[228:231], v118, s[100:101] offset:3328
	global_load_dwordx4 v[232:235], v119, s[100:101] offset:256
	s_add_u32 s100, s100, 0x20000
	s_addc_u32 s101, s101, 0
	s_waitcnt vmcnt(23)
; __device__ __forceinline__ void phase_resid(const Params& p, const float* g, bool first, bool last, int nsplit) {
;     ...
;         for (int sp = 0; sp < nsplit; ++sp) {
; #pragma unroll
;             for (int i = 0; i < 8; ++i) mv[i] += *(const f32x4*)(part + (size_t)(sp * 16 + gw) * DM + lane * 4 + 256 * i);
;         }
	v_pk_add_f32 v[110:111], v[110:111], v[120:121]
	v_pk_add_f32 v[112:113], v[112:113], v[122:123]
	global_load_dwordx4 v[120:123], v117, s[100:101] offset:1280
	s_waitcnt vmcnt(23)
	v_pk_add_f32 v[106:107], v[106:107], v[124:125]
	v_pk_add_f32 v[108:109], v[108:109], v[126:127]
	global_load_dwordx4 v[124:127], v117, s[100:101] offset:2304
	s_waitcnt vmcnt(23)
	v_pk_add_f32 v[102:103], v[102:103], v[128:129]
	v_pk_add_f32 v[104:105], v[104:105], v[130:131]
	global_load_dwordx4 v[128:131], v117, s[100:101] offset:3328
	s_waitcnt vmcnt(23)
	v_pk_add_f32 v[98:99], v[98:99], v[132:133]
	v_pk_add_f32 v[100:101], v[100:101], v[134:135]
	global_load_dwordx4 v[132:135], v118, s[100:101] offset:256
	s_waitcnt vmcnt(23)
	v_pk_add_f32 v[92:93], v[92:93], v[136:137]
	v_pk_add_f32 v[94:95], v[94:95], v[138:139]
	global_load_dwordx4 v[136:139], v118, s[100:101] offset:1280
	s_waitcnt vmcnt(23)
	v_pk_add_f32 v[84:85], v[84:85], v[140:141]
	v_pk_add_f32 v[86:87], v[86:87], v[142:143]
	global_load_dwordx4 v[140:143], v118, s[100:101] offset:2304
	s_waitcnt vmcnt(23)
	v_pk_add_f32 v[80:81], v[80:81], v[144:145]
	v_pk_add_f32 v[82:83], v[82:83], v[146:147]
	global_load_dwordx4 v[144:147], v118, s[100:101] offset:3328
	s_waitcnt vmcnt(23)
	v_pk_add_f32 v[88:89], v[88:89], v[152:153]
	v_pk_add_f32 v[90:91], v[90:91], v[154:155]
	global_load_dwordx4 v[152:155], v119, s[100:101] offset:256
	s_add_u32 s100, s100, 0x20000
	s_addc_u32 s101, s101, 0
	s_waitcnt vmcnt(23)
	v_pk_add_f32 v[110:111], v[110:111], v[156:157]
	v_pk_add_f32 v[112:113], v[112:113], v[158:159]
	global_load_dwordx4 v[156:159], v117, s[100:101] offset:1280
	s_waitcnt vmcnt(23)
	v_pk_add_f32 v[106:107], v[106:107], v[160:161]
	v_pk_add_f32 v[108:109], v[108:109], v[162:163]
	global_load_dwordx4 v[160:163], v117, s[100:101] offset:2304
	s_waitcnt vmcnt(23)
	v_pk_add_f32 v[102:103], v[102:103], v[164:165]
	v_pk_add_f32 v[104:105], v[104:105], v[166:167]
	global_load_dwordx4 v[164:167], v117, s[100:101] offset:3328
	s_waitcnt vmcnt(23)
	v_pk_add_f32 v[98:99], v[98:99], v[168:169]
	v_pk_add_f32 v[100:101], v[100:101], v[170:171]
	global_load_dwordx4 v[168:171], v118, s[100:101] offset:256
	s_waitcnt vmcnt(23)
	v_pk_add_f32 v[92:93], v[92:93], v[172:173]
	v_pk_add_f32 v[94:95], v[94:95], v[174:175]
	global_load_dwordx4 v[172:175], v118, s[100:101] offset:1280
	s_waitcnt vmcnt(23)
	v_pk_add_f32 v[84:85], v[84:85], v[176:177]
	v_pk_add_f32 v[86:87], v[86:87], v[178:179]
	global_load_dwordx4 v[176:179], v118, s[100:101] offset:2304
	s_waitcnt vmcnt(23)
	v_pk_add_f32 v[80:81], v[80:81], v[180:181]
	v_pk_add_f32 v[82:83], v[82:83], v[182:183]
	global_load_dwordx4 v[180:183], v118, s[100:101] offset:3328
	s_waitcnt vmcnt(23)
	v_pk_add_f32 v[88:89], v[88:89], v[184:185]
	v_pk_add_f32 v[90:91], v[90:91], v[186:187]
	global_load_dwordx4 v[184:187], v119, s[100:101] offset:256
	s_add_u32 s100, s100, 0x20000
	s_addc_u32 s101, s101, 0
	s_waitcnt vmcnt(23)
	v_pk_add_f32 v[110:111], v[110:111], v[188:189]
	v_pk_add_f32 v[112:113], v[112:113], v[190:191]
	global_load_dwordx4 v[188:191], v117, s[100:101] offset:1280
	s_waitcnt vmcnt(23)
	v_pk_add_f32 v[106:107], v[106:107], v[192:193]
	v_pk_add_f32 v[108:109], v[108:109], v[194:195]
	global_load_dwordx4 v[192:195], v117, s[100:101] offset:2304
	s_waitcnt vmcnt(23)
	v_pk_add_f32 v[102:103], v[102:103], v[196:197]
	v_pk_add_f32 v[104:105], v[104:105], v[198:199]
	global_load_dwordx4 v[196:199], v117, s[100:101] offset:3328
	s_waitcnt vmcnt(23)
	v_pk_add_f32 v[98:99], v[98:99], v[200:201]
	v_pk_add_f32 v[100:101], v[100:101], v[202:203]
	global_load_dwordx4 v[200:203], v118, s[100:101] offset:256
	s_waitcnt vmcnt(23)
	v_pk_add_f32 v[92:93], v[92:93], v[204:205]
	v_pk_add_f32 v[94:95], v[94:95], v[206:207]
	global_load_dwordx4 v[204:207], v118, s[100:101] offset:1280
	s_waitcnt vmcnt(23)
	v_pk_add_f32 v[84:85], v[84:85], v[224:225]
	v_pk_add_f32 v[86:87], v[86:87], v[226:227]
	global_load_dwordx4 v[224:227], v118, s[100:101] offset:2304
	s_waitcnt vmcnt(23)
	v_pk_add_f32 v[80:81], v[80:81], v[228:229]
	v_pk_add_f32 v[82:83], v[82:83], v[230:231]
	global_load_dwordx4 v[228:231], v118, s[100:101] offset:3328
	s_waitcnt vmcnt(23)
	v_pk_add_f32 v[88:89], v[88:89], v[232:233]
	v_pk_add_f32 v[90:91], v[90:91], v[234:235]
	global_load_dwordx4 v[232:235], v119, s[100:101] offset:256
	s_add_u32 s100, s100, 0x20000
	s_addc_u32 s101, s101, 0
	s_waitcnt vmcnt(23)
	v_pk_add_f32 v[110:111], v[110:111], v[120:121]
	v_pk_add_f32 v[112:113], v[112:113], v[122:123]
	global_load_dwordx4 v[120:123], v117, s[100:101] offset:1280
	s_waitcnt vmcnt(23)
	v_pk_add_f32 v[106:107], v[106:107], v[124:125]
	v_pk_add_f32 v[108:109], v[108:109], v[126:127]
	global_load_dwordx4 v[124:127], v117, s[100:101] offset:2304
	s_waitcnt vmcnt(23)
	v_pk_add_f32 v[102:103], v[102:103], v[128:129]
	v_pk_add_f32 v[104:105], v[104:105], v[130:131]
	global_load_dwordx4 v[128:131], v117, s[100:101] offset:3328
	s_waitcnt vmcnt(23)
	v_pk_add_f32 v[98:99], v[98:99], v[132:133]
	v_pk_add_f32 v[100:101], v[100:101], v[134:135]
	global_load_dwordx4 v[132:135], v118, s[100:101] offset:256
	s_waitcnt vmcnt(23)
	v_pk_add_f32 v[92:93], v[92:93], v[136:137]
	v_pk_add_f32 v[94:95], v[94:95], v[138:139]
	global_load_dwordx4 v[136:139], v118, s[100:101] offset:1280
	s_waitcnt vmcnt(23)
	v_pk_add_f32 v[84:85], v[84:85], v[140:141]
	v_pk_add_f32 v[86:87], v[86:87], v[142:143]
	global_load_dwordx4 v[140:143], v118, s[100:101] offset:2304
	s_waitcnt vmcnt(23)
	v_pk_add_f32 v[80:81], v[80:81], v[144:145]
	v_pk_add_f32 v[82:83], v[82:83], v[146:147]
	global_load_dwordx4 v[144:147], v118, s[100:101] offset:3328
	s_waitcnt vmcnt(23)
; __device__ __forceinline__ void phase_resid(const Params& p, const float* g, bool first, bool last, int nsplit) {
;     ...
;         for (int sp = 0; sp < nsplit; ++sp) {
; #pragma unroll
;             for (int i = 0; i < 8; ++i) mv[i] += *(const f32x4*)(part + (size_t)(sp * 16 + gw) * DM + lane * 4 + 256 * i);
;         }
	v_pk_add_f32 v[88:89], v[88:89], v[152:153]
	v_pk_add_f32 v[90:91], v[90:91], v[154:155]
	global_load_dwordx4 v[152:155], v119, s[100:101] offset:256
	s_add_u32 s100, s100, 0x20000
	s_addc_u32 s101, s101, 0
	s_waitcnt vmcnt(23)
	v_pk_add_f32 v[110:111], v[110:111], v[156:157]
	v_pk_add_f32 v[112:113], v[112:113], v[158:159]
	global_load_dwordx4 v[156:159], v117, s[100:101] offset:1280
	s_waitcnt vmcnt(23)
	v_pk_add_f32 v[106:107], v[106:107], v[160:161]
	v_pk_add_f32 v[108:109], v[108:109], v[162:163]
	global_load_dwordx4 v[160:163], v117, s[100:101] offset:2304
	s_waitcnt vmcnt(23)
	v_pk_add_f32 v[102:103], v[102:103], v[164:165]
	v_pk_add_f32 v[104:105], v[104:105], v[166:167]
	global_load_dwordx4 v[164:167], v117, s[100:101] offset:3328
	s_waitcnt vmcnt(23)
	v_pk_add_f32 v[98:99], v[98:99], v[168:169]
	v_pk_add_f32 v[100:101], v[100:101], v[170:171]
	global_load_dwordx4 v[168:171], v118, s[100:101] offset:256
	s_waitcnt vmcnt(23)
	v_pk_add_f32 v[92:93], v[92:93], v[172:173]
	v_pk_add_f32 v[94:95], v[94:95], v[174:175]
	global_load_dwordx4 v[172:175], v118, s[100:101] offset:1280
	s_waitcnt vmcnt(23)
	v_pk_add_f32 v[84:85], v[84:85], v[176:177]
	v_pk_add_f32 v[86:87], v[86:87], v[178:179]
	global_load_dwordx4 v[176:179], v118, s[100:101] offset:2304
	s_waitcnt vmcnt(23)
	v_pk_add_f32 v[80:81], v[80:81], v[180:181]
	v_pk_add_f32 v[82:83], v[82:83], v[182:183]
	global_load_dwordx4 v[180:183], v118, s[100:101] offset:3328
	s_waitcnt vmcnt(23)
	v_pk_add_f32 v[88:89], v[88:89], v[184:185]
	v_pk_add_f32 v[90:91], v[90:91], v[186:187]
	global_load_dwordx4 v[184:187], v119, s[100:101] offset:256
	s_add_u32 s100, s100, 0x20000
	s_addc_u32 s101, s101, 0
	s_waitcnt vmcnt(23)
	v_pk_add_f32 v[110:111], v[110:111], v[188:189]
	v_pk_add_f32 v[112:113], v[112:113], v[190:191]
	global_load_dwordx4 v[188:191], v117, s[100:101] offset:1280
	s_waitcnt vmcnt(23)
	v_pk_add_f32 v[106:107], v[106:107], v[192:193]
	v_pk_add_f32 v[108:109], v[108:109], v[194:195]
	global_load_dwordx4 v[192:195], v117, s[100:101] offset:2304
	s_waitcnt vmcnt(23)
	v_pk_add_f32 v[102:103], v[102:103], v[196:197]
	v_pk_add_f32 v[104:105], v[104:105], v[198:199]
	global_load_dwordx4 v[196:199], v117, s[100:101] offset:3328
	s_waitcnt vmcnt(23)
	v_pk_add_f32 v[98:99], v[98:99], v[200:201]
	v_pk_add_f32 v[100:101], v[100:101], v[202:203]
	global_load_dwordx4 v[200:203], v118, s[100:101] offset:256
	s_waitcnt vmcnt(23)
	v_pk_add_f32 v[92:93], v[92:93], v[204:205]
	v_pk_add_f32 v[94:95], v[94:95], v[206:207]
	global_load_dwordx4 v[204:207], v118, s[100:101] offset:1280
	s_waitcnt vmcnt(23)
	v_pk_add_f32 v[84:85], v[84:85], v[224:225]
	v_pk_add_f32 v[86:87], v[86:87], v[226:227]
	global_load_dwordx4 v[224:227], v118, s[100:101] offset:2304
	s_waitcnt vmcnt(23)
	v_pk_add_f32 v[80:81], v[80:81], v[228:229]
	v_pk_add_f32 v[82:83], v[82:83], v[230:231]
	global_load_dwordx4 v[228:231], v118, s[100:101] offset:3328
	s_waitcnt vmcnt(23)
	v_pk_add_f32 v[88:89], v[88:89], v[232:233]
	v_pk_add_f32 v[90:91], v[90:91], v[234:235]
	global_load_dwordx4 v[232:235], v119, s[100:101] offset:256
	s_add_u32 s100, s100, 0x20000
	s_addc_u32 s101, s101, 0
	s_waitcnt vmcnt(23)
	v_pk_add_f32 v[110:111], v[110:111], v[120:121]
	v_pk_add_f32 v[112:113], v[112:113], v[122:123]
	global_load_dwordx4 v[120:123], v117, s[100:101] offset:1280
	s_waitcnt vmcnt(23)
	v_pk_add_f32 v[106:107], v[106:107], v[124:125]
	v_pk_add_f32 v[108:109], v[108:109], v[126:127]
	global_load_dwordx4 v[124:127], v117, s[100:101] offset:2304
	s_waitcnt vmcnt(23)
	v_pk_add_f32 v[102:103], v[102:103], v[128:129]
	v_pk_add_f32 v[104:105], v[104:105], v[130:131]
	global_load_dwordx4 v[128:131], v117, s[100:101] offset:3328
	s_waitcnt vmcnt(23)
	v_pk_add_f32 v[98:99], v[98:99], v[132:133]
	v_pk_add_f32 v[100:101], v[100:101], v[134:135]
	global_load_dwordx4 v[132:135], v118, s[100:101] offset:256
	s_waitcnt vmcnt(23)
	v_pk_add_f32 v[92:93], v[92:93], v[136:137]
	v_pk_add_f32 v[94:95], v[94:95], v[138:139]
	global_load_dwordx4 v[136:139], v118, s[100:101] offset:1280
	s_waitcnt vmcnt(23)
	v_pk_add_f32 v[84:85], v[84:85], v[140:141]
	v_pk_add_f32 v[86:87], v[86:87], v[142:143]
	global_load_dwordx4 v[140:143], v118, s[100:101] offset:2304
	s_waitcnt vmcnt(23)
	v_pk_add_f32 v[80:81], v[80:81], v[144:145]
	v_pk_add_f32 v[82:83], v[82:83], v[146:147]
	global_load_dwordx4 v[144:147], v118, s[100:101] offset:3328
	s_waitcnt vmcnt(23)
	v_pk_add_f32 v[88:89], v[88:89], v[152:153]
	v_pk_add_f32 v[90:91], v[90:91], v[154:155]
	global_load_dwordx4 v[152:155], v119, s[100:101] offset:256
	s_add_u32 s100, s100, 0x20000
	s_addc_u32 s101, s101, 0
	s_waitcnt vmcnt(23)
	v_pk_add_f32 v[110:111], v[110:111], v[156:157]
	v_pk_add_f32 v[112:113], v[112:113], v[158:159]
	global_load_dwordx4 v[156:159], v117, s[100:101] offset:1280
	s_waitcnt vmcnt(23)
	v_pk_add_f32 v[106:107], v[106:107], v[160:161]
	v_pk_add_f32 v[108:109], v[108:109], v[162:163]
	global_load_dwordx4 v[160:163], v117, s[100:101] offset:2304
	s_waitcnt vmcnt(23)
	v_pk_add_f32 v[102:103], v[102:103], v[164:165]
	v_pk_add_f32 v[104:105], v[104:105], v[166:167]
	global_load_dwordx4 v[164:167], v117, s[100:101] offset:3328
	s_waitcnt vmcnt(23)
	v_pk_add_f32 v[98:99], v[98:99], v[168:169]
	v_pk_add_f32 v[100:101], v[100:101], v[170:171]
	global_load_dwordx4 v[168:171], v118, s[100:101] offset:256
	s_waitcnt vmcnt(23)
	v_pk_add_f32 v[92:93], v[92:93], v[172:173]
	v_pk_add_f32 v[94:95], v[94:95], v[174:175]
	global_load_dwordx4 v[172:175], v118, s[100:101] offset:1280
	s_waitcnt vmcnt(23)
	v_pk_add_f32 v[84:85], v[84:85], v[176:177]
	v_pk_add_f32 v[86:87], v[86:87], v[178:179]
	global_load_dwordx4 v[176:179], v118, s[100:101] offset:2304
	s_waitcnt vmcnt(23)
; __device__ __forceinline__ void phase_resid(const Params& p, const float* g, bool first, bool last, int nsplit) {
;     ...
;         for (int sp = 0; sp < nsplit; ++sp) {
; #pragma unroll
;             for (int i = 0; i < 8; ++i) mv[i] += *(const f32x4*)(part + (size_t)(sp * 16 + gw) * DM + lane * 4 + 256 * i);
;         }
	v_pk_add_f32 v[80:81], v[80:81], v[180:181]
	v_pk_add_f32 v[82:83], v[82:83], v[182:183]
	global_load_dwordx4 v[180:183], v118, s[100:101] offset:3328
	s_waitcnt vmcnt(23)
	v_pk_add_f32 v[88:89], v[88:89], v[184:185]
	v_pk_add_f32 v[90:91], v[90:91], v[186:187]
	global_load_dwordx4 v[184:187], v119, s[100:101] offset:256
	s_add_u32 s100, s100, 0x20000
	s_addc_u32 s101, s101, 0
	s_waitcnt vmcnt(23)
	v_pk_add_f32 v[110:111], v[110:111], v[188:189]
	v_pk_add_f32 v[112:113], v[112:113], v[190:191]
	global_load_dwordx4 v[188:191], v117, s[100:101] offset:1280
	s_waitcnt vmcnt(23)
	v_pk_add_f32 v[106:107], v[106:107], v[192:193]
	v_pk_add_f32 v[108:109], v[108:109], v[194:195]
	global_load_dwordx4 v[192:195], v117, s[100:101] offset:2304
	s_waitcnt vmcnt(23)
	v_pk_add_f32 v[102:103], v[102:103], v[196:197]
	v_pk_add_f32 v[104:105], v[104:105], v[198:199]
	global_load_dwordx4 v[196:199], v117, s[100:101] offset:3328
	s_waitcnt vmcnt(23)
	v_pk_add_f32 v[98:99], v[98:99], v[200:201]
	v_pk_add_f32 v[100:101], v[100:101], v[202:203]
	global_load_dwordx4 v[200:203], v118, s[100:101] offset:256
	s_waitcnt vmcnt(23)
	v_pk_add_f32 v[92:93], v[92:93], v[204:205]
	v_pk_add_f32 v[94:95], v[94:95], v[206:207]
	global_load_dwordx4 v[204:207], v118, s[100:101] offset:1280
	s_waitcnt vmcnt(23)
	v_pk_add_f32 v[84:85], v[84:85], v[224:225]
	v_pk_add_f32 v[86:87], v[86:87], v[226:227]
	global_load_dwordx4 v[224:227], v118, s[100:101] offset:2304
	s_waitcnt vmcnt(23)
	v_pk_add_f32 v[80:81], v[80:81], v[228:229]
	v_pk_add_f32 v[82:83], v[82:83], v[230:231]
	global_load_dwordx4 v[228:231], v118, s[100:101] offset:3328
	s_waitcnt vmcnt(23)
	v_pk_add_f32 v[88:89], v[88:89], v[232:233]
	v_pk_add_f32 v[90:91], v[90:91], v[234:235]
	global_load_dwordx4 v[232:235], v119, s[100:101] offset:256
	s_add_u32 s100, s100, 0x20000
	s_addc_u32 s101, s101, 0
	s_waitcnt vmcnt(23)
	v_pk_add_f32 v[110:111], v[110:111], v[120:121]
	v_pk_add_f32 v[112:113], v[112:113], v[122:123]
	global_load_dwordx4 v[120:123], v117, s[100:101] offset:1280
	s_waitcnt vmcnt(23)
	v_pk_add_f32 v[106:107], v[106:107], v[124:125]
	v_pk_add_f32 v[108:109], v[108:109], v[126:127]
	global_load_dwordx4 v[124:127], v117, s[100:101] offset:2304
	s_waitcnt vmcnt(23)
	v_pk_add_f32 v[102:103], v[102:103], v[128:129]
	v_pk_add_f32 v[104:105], v[104:105], v[130:131]
	global_load_dwordx4 v[128:131], v117, s[100:101] offset:3328
	s_waitcnt vmcnt(23)
	v_pk_add_f32 v[98:99], v[98:99], v[132:133]
	v_pk_add_f32 v[100:101], v[100:101], v[134:135]
	global_load_dwordx4 v[132:135], v118, s[100:101] offset:256
	s_waitcnt vmcnt(23)
	v_pk_add_f32 v[92:93], v[92:93], v[136:137]
	v_pk_add_f32 v[94:95], v[94:95], v[138:139]
	global_load_dwordx4 v[136:139], v118, s[100:101] offset:1280
	s_waitcnt vmcnt(23)
	v_pk_add_f32 v[84:85], v[84:85], v[140:141]
	v_pk_add_f32 v[86:87], v[86:87], v[142:143]
	global_load_dwordx4 v[140:143], v118, s[100:101] offset:2304
	s_waitcnt vmcnt(23)
	v_pk_add_f32 v[80:81], v[80:81], v[144:145]
	v_pk_add_f32 v[82:83], v[82:83], v[146:147]
	global_load_dwordx4 v[144:147], v118, s[100:101] offset:3328
	s_waitcnt vmcnt(23)
	v_pk_add_f32 v[88:89], v[88:89], v[152:153]
	v_pk_add_f32 v[90:91], v[90:91], v[154:155]
	global_load_dwordx4 v[152:155], v119, s[100:101] offset:256
	s_add_u32 s100, s100, 0x20000
	s_addc_u32 s101, s101, 0
	s_waitcnt vmcnt(23)
	v_pk_add_f32 v[110:111], v[110:111], v[156:157]
	v_pk_add_f32 v[112:113], v[112:113], v[158:159]
	global_load_dwordx4 v[156:159], v117, s[100:101] offset:1280
	s_waitcnt vmcnt(23)
	v_pk_add_f32 v[106:107], v[106:107], v[160:161]
	v_pk_add_f32 v[108:109], v[108:109], v[162:163]
	global_load_dwordx4 v[160:163], v117, s[100:101] offset:2304
	s_waitcnt vmcnt(23)
	v_pk_add_f32 v[102:103], v[102:103], v[164:165]
	v_pk_add_f32 v[104:105], v[104:105], v[166:167]
	global_load_dwordx4 v[164:167], v117, s[100:101] offset:3328
	s_waitcnt vmcnt(23)
	v_pk_add_f32 v[98:99], v[98:99], v[168:169]
	v_pk_add_f32 v[100:101], v[100:101], v[170:171]
	global_load_dwordx4 v[168:171], v118, s[100:101] offset:256
	s_waitcnt vmcnt(23)
	v_pk_add_f32 v[92:93], v[92:93], v[172:173]
	v_pk_add_f32 v[94:95], v[94:95], v[174:175]
	global_load_dwordx4 v[172:175], v118, s[100:101] offset:1280
	s_waitcnt vmcnt(23)
	v_pk_add_f32 v[84:85], v[84:85], v[176:177]
	v_pk_add_f32 v[86:87], v[86:87], v[178:179]
	global_load_dwordx4 v[176:179], v118, s[100:101] offset:2304
	s_waitcnt vmcnt(23)
	v_pk_add_f32 v[80:81], v[80:81], v[180:181]
	v_pk_add_f32 v[82:83], v[82:83], v[182:183]
	global_load_dwordx4 v[180:183], v118, s[100:101] offset:3328
	s_waitcnt vmcnt(23)
	v_pk_add_f32 v[88:89], v[88:89], v[184:185]
	v_pk_add_f32 v[90:91], v[90:91], v[186:187]
	global_load_dwordx4 v[184:187], v119, s[100:101] offset:256
	s_add_u32 s100, s100, 0x20000
	s_addc_u32 s101, s101, 0
	s_waitcnt vmcnt(23)
	v_pk_add_f32 v[110:111], v[110:111], v[188:189]
	v_pk_add_f32 v[112:113], v[112:113], v[190:191]
	global_load_dwordx4 v[188:191], v117, s[100:101] offset:1280
	s_waitcnt vmcnt(23)
	v_pk_add_f32 v[106:107], v[106:107], v[192:193]
	v_pk_add_f32 v[108:109], v[108:109], v[194:195]
	global_load_dwordx4 v[192:195], v117, s[100:101] offset:2304
	s_waitcnt vmcnt(23)
	v_pk_add_f32 v[102:103], v[102:103], v[196:197]
	v_pk_add_f32 v[104:105], v[104:105], v[198:199]
	global_load_dwordx4 v[196:199], v117, s[100:101] offset:3328
	s_waitcnt vmcnt(23)
	v_pk_add_f32 v[98:99], v[98:99], v[200:201]
	v_pk_add_f32 v[100:101], v[100:101], v[202:203]
	global_load_dwordx4 v[200:203], v118, s[100:101] offset:256
	s_waitcnt vmcnt(23)
	v_pk_add_f32 v[92:93], v[92:93], v[204:205]
	v_pk_add_f32 v[94:95], v[94:95], v[206:207]
	global_load_dwordx4 v[204:207], v118, s[100:101] offset:1280
	s_waitcnt vmcnt(23)
; __device__ __forceinline__ void phase_resid(const Params& p, const float* g, bool first, bool last, int nsplit) {
;     ...
;         for (int sp = 0; sp < nsplit; ++sp) {
; #pragma unroll
;             for (int i = 0; i < 8; ++i) mv[i] += *(const f32x4*)(part + (size_t)(sp * 16 + gw) * DM + lane * 4 + 256 * i);
;         }
	v_pk_add_f32 v[84:85], v[84:85], v[224:225]
	v_pk_add_f32 v[86:87], v[86:87], v[226:227]
	global_load_dwordx4 v[224:227], v118, s[100:101] offset:2304
	s_waitcnt vmcnt(23)
	v_pk_add_f32 v[80:81], v[80:81], v[228:229]
	v_pk_add_f32 v[82:83], v[82:83], v[230:231]
	global_load_dwordx4 v[228:231], v118, s[100:101] offset:3328
	s_waitcnt vmcnt(23)
	v_pk_add_f32 v[88:89], v[88:89], v[232:233]
	v_pk_add_f32 v[90:91], v[90:91], v[234:235]
	global_load_dwordx4 v[232:235], v119, s[100:101] offset:256
	s_add_u32 s100, s100, 0x20000
	s_addc_u32 s101, s101, 0
	s_waitcnt vmcnt(23)
	v_pk_add_f32 v[110:111], v[110:111], v[120:121]
	v_pk_add_f32 v[112:113], v[112:113], v[122:123]
	global_load_dwordx4 v[120:123], v117, s[100:101] offset:1280
	s_waitcnt vmcnt(23)
	v_pk_add_f32 v[106:107], v[106:107], v[124:125]
	v_pk_add_f32 v[108:109], v[108:109], v[126:127]
	global_load_dwordx4 v[124:127], v117, s[100:101] offset:2304
	s_waitcnt vmcnt(23)
	v_pk_add_f32 v[102:103], v[102:103], v[128:129]
	v_pk_add_f32 v[104:105], v[104:105], v[130:131]
	global_load_dwordx4 v[128:131], v117, s[100:101] offset:3328
	s_waitcnt vmcnt(23)
	v_pk_add_f32 v[98:99], v[98:99], v[132:133]
	v_pk_add_f32 v[100:101], v[100:101], v[134:135]
	global_load_dwordx4 v[132:135], v118, s[100:101] offset:256
	s_waitcnt vmcnt(23)
	v_pk_add_f32 v[92:93], v[92:93], v[136:137]
	v_pk_add_f32 v[94:95], v[94:95], v[138:139]
	global_load_dwordx4 v[136:139], v118, s[100:101] offset:1280
	s_waitcnt vmcnt(23)
	v_pk_add_f32 v[84:85], v[84:85], v[140:141]
	v_pk_add_f32 v[86:87], v[86:87], v[142:143]
	global_load_dwordx4 v[140:143], v118, s[100:101] offset:2304
	s_waitcnt vmcnt(23)
	v_pk_add_f32 v[80:81], v[80:81], v[144:145]
	v_pk_add_f32 v[82:83], v[82:83], v[146:147]
	global_load_dwordx4 v[144:147], v118, s[100:101] offset:3328
	s_waitcnt vmcnt(23)
	v_pk_add_f32 v[88:89], v[88:89], v[152:153]
	v_pk_add_f32 v[90:91], v[90:91], v[154:155]
	global_load_dwordx4 v[152:155], v119, s[100:101] offset:256
	s_add_u32 s100, s100, 0x20000
	s_addc_u32 s101, s101, 0
	s_waitcnt vmcnt(23)
	v_pk_add_f32 v[110:111], v[110:111], v[156:157]
	v_pk_add_f32 v[112:113], v[112:113], v[158:159]
	global_load_dwordx4 v[156:159], v117, s[100:101] offset:1280
	s_waitcnt vmcnt(23)
	v_pk_add_f32 v[106:107], v[106:107], v[160:161]
	v_pk_add_f32 v[108:109], v[108:109], v[162:163]
	global_load_dwordx4 v[160:163], v117, s[100:101] offset:2304
	s_waitcnt vmcnt(23)
	v_pk_add_f32 v[102:103], v[102:103], v[164:165]
	v_pk_add_f32 v[104:105], v[104:105], v[166:167]
	global_load_dwordx4 v[164:167], v117, s[100:101] offset:3328
	s_waitcnt vmcnt(23)
	v_pk_add_f32 v[98:99], v[98:99], v[168:169]
	v_pk_add_f32 v[100:101], v[100:101], v[170:171]
	global_load_dwordx4 v[168:171], v118, s[100:101] offset:256
	s_waitcnt vmcnt(23)
	v_pk_add_f32 v[92:93], v[92:93], v[172:173]
	v_pk_add_f32 v[94:95], v[94:95], v[174:175]
	global_load_dwordx4 v[172:175], v118, s[100:101] offset:1280
	s_waitcnt vmcnt(23)
	v_pk_add_f32 v[84:85], v[84:85], v[176:177]
	v_pk_add_f32 v[86:87], v[86:87], v[178:179]
	global_load_dwordx4 v[176:179], v118, s[100:101] offset:2304
	s_waitcnt vmcnt(23)
	v_pk_add_f32 v[80:81], v[80:81], v[180:181]
	v_pk_add_f32 v[82:83], v[82:83], v[182:183]
	global_load_dwordx4 v[180:183], v118, s[100:101] offset:3328
	s_waitcnt vmcnt(23)
	v_pk_add_f32 v[88:89], v[88:89], v[184:185]
	v_pk_add_f32 v[90:91], v[90:91], v[186:187]
	global_load_dwordx4 v[184:187], v119, s[100:101] offset:256
	s_add_u32 s100, s100, 0x20000
	s_addc_u32 s101, s101, 0
	s_waitcnt vmcnt(23)
	v_pk_add_f32 v[110:111], v[110:111], v[188:189]
	v_pk_add_f32 v[112:113], v[112:113], v[190:191]
	global_load_dwordx4 v[188:191], v117, s[100:101] offset:1280
	s_waitcnt vmcnt(23)
	v_pk_add_f32 v[106:107], v[106:107], v[192:193]
	v_pk_add_f32 v[108:109], v[108:109], v[194:195]
	global_load_dwordx4 v[192:195], v117, s[100:101] offset:2304
	s_waitcnt vmcnt(23)
	v_pk_add_f32 v[102:103], v[102:103], v[196:197]
	v_pk_add_f32 v[104:105], v[104:105], v[198:199]
	global_load_dwordx4 v[196:199], v117, s[100:101] offset:3328
	s_waitcnt vmcnt(23)
	v_pk_add_f32 v[98:99], v[98:99], v[200:201]
	v_pk_add_f32 v[100:101], v[100:101], v[202:203]
	global_load_dwordx4 v[200:203], v118, s[100:101] offset:256
	s_waitcnt vmcnt(23)
	v_pk_add_f32 v[92:93], v[92:93], v[204:205]
	v_pk_add_f32 v[94:95], v[94:95], v[206:207]
	global_load_dwordx4 v[204:207], v118, s[100:101] offset:1280
	s_waitcnt vmcnt(23)
	v_pk_add_f32 v[84:85], v[84:85], v[224:225]
	v_pk_add_f32 v[86:87], v[86:87], v[226:227]
	global_load_dwordx4 v[224:227], v118, s[100:101] offset:2304
	s_waitcnt vmcnt(23)
	v_pk_add_f32 v[80:81], v[80:81], v[228:229]
	v_pk_add_f32 v[82:83], v[82:83], v[230:231]
	global_load_dwordx4 v[228:231], v118, s[100:101] offset:3328
	s_waitcnt vmcnt(23)
	v_pk_add_f32 v[88:89], v[88:89], v[232:233]
	v_pk_add_f32 v[90:91], v[90:91], v[234:235]
	global_load_dwordx4 v[232:235], v119, s[100:101] offset:256
	s_add_u32 s100, s100, 0x20000
	s_addc_u32 s101, s101, 0
	s_waitcnt vmcnt(23)
	v_pk_add_f32 v[110:111], v[110:111], v[120:121]
	v_pk_add_f32 v[112:113], v[112:113], v[122:123]
	global_load_dwordx4 v[120:123], v117, s[100:101] offset:1280
	s_waitcnt vmcnt(23)
	v_pk_add_f32 v[106:107], v[106:107], v[124:125]
	v_pk_add_f32 v[108:109], v[108:109], v[126:127]
	global_load_dwordx4 v[124:127], v117, s[100:101] offset:2304
	s_waitcnt vmcnt(23)
	v_pk_add_f32 v[102:103], v[102:103], v[128:129]
	v_pk_add_f32 v[104:105], v[104:105], v[130:131]
	global_load_dwordx4 v[128:131], v117, s[100:101] offset:3328
	s_waitcnt vmcnt(23)
	v_pk_add_f32 v[98:99], v[98:99], v[132:133]
	v_pk_add_f32 v[100:101], v[100:101], v[134:135]
	global_load_dwordx4 v[132:135], v118, s[100:101] offset:256
	s_waitcnt vmcnt(23)
; __device__ __forceinline__ void phase_resid(const Params& p, const float* g, bool first, bool last, int nsplit) {
;     ...
;         for (int sp = 0; sp < nsplit; ++sp) {
; #pragma unroll
;             for (int i = 0; i < 8; ++i) mv[i] += *(const f32x4*)(part + (size_t)(sp * 16 + gw) * DM + lane * 4 + 256 * i);
;         }
	v_pk_add_f32 v[92:93], v[92:93], v[136:137]
	v_pk_add_f32 v[94:95], v[94:95], v[138:139]
	global_load_dwordx4 v[136:139], v118, s[100:101] offset:1280
	s_waitcnt vmcnt(23)
	v_pk_add_f32 v[84:85], v[84:85], v[140:141]
	v_pk_add_f32 v[86:87], v[86:87], v[142:143]
	global_load_dwordx4 v[140:143], v118, s[100:101] offset:2304
	s_waitcnt vmcnt(23)
	v_pk_add_f32 v[80:81], v[80:81], v[144:145]
	v_pk_add_f32 v[82:83], v[82:83], v[146:147]
	global_load_dwordx4 v[144:147], v118, s[100:101] offset:3328
	s_waitcnt vmcnt(23)
	v_pk_add_f32 v[88:89], v[88:89], v[152:153]
	v_pk_add_f32 v[90:91], v[90:91], v[154:155]
	global_load_dwordx4 v[152:155], v119, s[100:101] offset:256
	s_add_u32 s100, s100, 0x20000
	s_addc_u32 s101, s101, 0
	s_waitcnt vmcnt(23)
	v_pk_add_f32 v[110:111], v[110:111], v[156:157]
	v_pk_add_f32 v[112:113], v[112:113], v[158:159]
	global_load_dwordx4 v[156:159], v117, s[100:101] offset:1280
	s_waitcnt vmcnt(23)
	v_pk_add_f32 v[106:107], v[106:107], v[160:161]
	v_pk_add_f32 v[108:109], v[108:109], v[162:163]
	global_load_dwordx4 v[160:163], v117, s[100:101] offset:2304
	s_waitcnt vmcnt(23)
	v_pk_add_f32 v[102:103], v[102:103], v[164:165]
	v_pk_add_f32 v[104:105], v[104:105], v[166:167]
	global_load_dwordx4 v[164:167], v117, s[100:101] offset:3328
	s_waitcnt vmcnt(23)
	v_pk_add_f32 v[98:99], v[98:99], v[168:169]
	v_pk_add_f32 v[100:101], v[100:101], v[170:171]
	global_load_dwordx4 v[168:171], v118, s[100:101] offset:256
	s_waitcnt vmcnt(23)
	v_pk_add_f32 v[92:93], v[92:93], v[172:173]
	v_pk_add_f32 v[94:95], v[94:95], v[174:175]
	global_load_dwordx4 v[172:175], v118, s[100:101] offset:1280
	s_waitcnt vmcnt(23)
	v_pk_add_f32 v[84:85], v[84:85], v[176:177]
	v_pk_add_f32 v[86:87], v[86:87], v[178:179]
	global_load_dwordx4 v[176:179], v118, s[100:101] offset:2304
	s_waitcnt vmcnt(23)
	v_pk_add_f32 v[80:81], v[80:81], v[180:181]
	v_pk_add_f32 v[82:83], v[82:83], v[182:183]
	global_load_dwordx4 v[180:183], v118, s[100:101] offset:3328
	s_waitcnt vmcnt(23)
	v_pk_add_f32 v[88:89], v[88:89], v[184:185]
	v_pk_add_f32 v[90:91], v[90:91], v[186:187]
	global_load_dwordx4 v[184:187], v119, s[100:101] offset:256
	s_add_u32 s100, s100, 0x20000
	s_addc_u32 s101, s101, 0
	s_waitcnt vmcnt(23)
	v_pk_add_f32 v[110:111], v[110:111], v[188:189]
	v_pk_add_f32 v[112:113], v[112:113], v[190:191]
	global_load_dwordx4 v[188:191], v117, s[100:101] offset:1280
	s_waitcnt vmcnt(23)
	v_pk_add_f32 v[106:107], v[106:107], v[192:193]
	v_pk_add_f32 v[108:109], v[108:109], v[194:195]
	global_load_dwordx4 v[192:195], v117, s[100:101] offset:2304
	s_waitcnt vmcnt(23)
	v_pk_add_f32 v[102:103], v[102:103], v[196:197]
	v_pk_add_f32 v[104:105], v[104:105], v[198:199]
	global_load_dwordx4 v[196:199], v117, s[100:101] offset:3328
	s_waitcnt vmcnt(23)
	v_pk_add_f32 v[98:99], v[98:99], v[200:201]
	v_pk_add_f32 v[100:101], v[100:101], v[202:203]
	global_load_dwordx4 v[200:203], v118, s[100:101] offset:256
	s_waitcnt vmcnt(23)
	v_pk_add_f32 v[92:93], v[92:93], v[204:205]
	v_pk_add_f32 v[94:95], v[94:95], v[206:207]
	global_load_dwordx4 v[204:207], v118, s[100:101] offset:1280
	s_waitcnt vmcnt(23)
	v_pk_add_f32 v[84:85], v[84:85], v[224:225]
	v_pk_add_f32 v[86:87], v[86:87], v[226:227]
	global_load_dwordx4 v[224:227], v118, s[100:101] offset:2304
	s_waitcnt vmcnt(23)
	v_pk_add_f32 v[80:81], v[80:81], v[228:229]
	v_pk_add_f32 v[82:83], v[82:83], v[230:231]
	global_load_dwordx4 v[228:231], v118, s[100:101] offset:3328
	s_waitcnt vmcnt(23)
	v_pk_add_f32 v[88:89], v[88:89], v[232:233]
	v_pk_add_f32 v[90:91], v[90:91], v[234:235]
	global_load_dwordx4 v[232:235], v119, s[100:101] offset:256
	s_add_u32 s100, s100, 0x20000
	s_addc_u32 s101, s101, 0
	s_waitcnt vmcnt(23)
	v_pk_add_f32 v[110:111], v[110:111], v[120:121]
	v_pk_add_f32 v[112:113], v[112:113], v[122:123]
	global_load_dwordx4 v[120:123], v117, s[100:101] offset:1280
	s_waitcnt vmcnt(23)
	v_pk_add_f32 v[106:107], v[106:107], v[124:125]
	v_pk_add_f32 v[108:109], v[108:109], v[126:127]
	global_load_dwordx4 v[124:127], v117, s[100:101] offset:2304
	s_waitcnt vmcnt(23)
	v_pk_add_f32 v[102:103], v[102:103], v[128:129]
	v_pk_add_f32 v[104:105], v[104:105], v[130:131]
	global_load_dwordx4 v[128:131], v117, s[100:101] offset:3328
	s_waitcnt vmcnt(23)
	v_pk_add_f32 v[98:99], v[98:99], v[132:133]
	v_pk_add_f32 v[100:101], v[100:101], v[134:135]
	global_load_dwordx4 v[132:135], v118, s[100:101] offset:256
	s_waitcnt vmcnt(23)
	v_pk_add_f32 v[92:93], v[92:93], v[136:137]
	v_pk_add_f32 v[94:95], v[94:95], v[138:139]
	global_load_dwordx4 v[136:139], v118, s[100:101] offset:1280
	s_waitcnt vmcnt(23)
	v_pk_add_f32 v[84:85], v[84:85], v[140:141]
	v_pk_add_f32 v[86:87], v[86:87], v[142:143]
	global_load_dwordx4 v[140:143], v118, s[100:101] offset:2304
	s_waitcnt vmcnt(23)
	v_pk_add_f32 v[80:81], v[80:81], v[144:145]
	v_pk_add_f32 v[82:83], v[82:83], v[146:147]
	global_load_dwordx4 v[144:147], v118, s[100:101] offset:3328
	s_waitcnt vmcnt(23)
	v_pk_add_f32 v[88:89], v[88:89], v[152:153]
	v_pk_add_f32 v[90:91], v[90:91], v[154:155]
	global_load_dwordx4 v[152:155], v119, s[100:101] offset:256
	s_waitcnt vmcnt(23)
	v_pk_add_f32 v[110:111], v[110:111], v[156:157]
	v_pk_add_f32 v[112:113], v[112:113], v[158:159]
	s_waitcnt vmcnt(22)
	v_pk_add_f32 v[106:107], v[106:107], v[160:161]
	v_pk_add_f32 v[108:109], v[108:109], v[162:163]
	s_waitcnt vmcnt(21)
	v_pk_add_f32 v[102:103], v[102:103], v[164:165]
	v_pk_add_f32 v[104:105], v[104:105], v[166:167]
	s_waitcnt vmcnt(20)
	v_pk_add_f32 v[98:99], v[98:99], v[168:169]
	v_pk_add_f32 v[100:101], v[100:101], v[170:171]
	s_waitcnt vmcnt(19)
	v_pk_add_f32 v[92:93], v[92:93], v[172:173]
	v_pk_add_f32 v[94:95], v[94:95], v[174:175]
	s_waitcnt vmcnt(18)
; __device__ __forceinline__ void phase_resid(const Params& p, const float* g, bool first, bool last, int nsplit) {
;     ...
;         for (int sp = 0; sp < nsplit; ++sp) {
; #pragma unroll
;             for (int i = 0; i < 8; ++i) mv[i] += *(const f32x4*)(part + (size_t)(sp * 16 + gw) * DM + lane * 4 + 256 * i);
;         }
	v_pk_add_f32 v[84:85], v[84:85], v[176:177]
	v_pk_add_f32 v[86:87], v[86:87], v[178:179]
	s_waitcnt vmcnt(17)
	v_pk_add_f32 v[80:81], v[80:81], v[180:181]
	v_pk_add_f32 v[82:83], v[82:83], v[182:183]
	s_waitcnt vmcnt(16)
	v_pk_add_f32 v[88:89], v[88:89], v[184:185]
	v_pk_add_f32 v[90:91], v[90:91], v[186:187]
	s_waitcnt vmcnt(15)
	v_pk_add_f32 v[110:111], v[110:111], v[188:189]
	v_pk_add_f32 v[112:113], v[112:113], v[190:191]
	s_waitcnt vmcnt(14)
	v_pk_add_f32 v[106:107], v[106:107], v[192:193]
	v_pk_add_f32 v[108:109], v[108:109], v[194:195]
	s_waitcnt vmcnt(13)
	v_pk_add_f32 v[102:103], v[102:103], v[196:197]
	v_pk_add_f32 v[104:105], v[104:105], v[198:199]
	s_waitcnt vmcnt(12)
	v_pk_add_f32 v[98:99], v[98:99], v[200:201]
	v_pk_add_f32 v[100:101], v[100:101], v[202:203]
	s_waitcnt vmcnt(11)
	v_pk_add_f32 v[92:93], v[92:93], v[204:205]
	v_pk_add_f32 v[94:95], v[94:95], v[206:207]
	s_waitcnt vmcnt(10)
	v_pk_add_f32 v[84:85], v[84:85], v[224:225]
	v_pk_add_f32 v[86:87], v[86:87], v[226:227]
	s_waitcnt vmcnt(9)
	v_pk_add_f32 v[80:81], v[80:81], v[228:229]
	v_pk_add_f32 v[82:83], v[82:83], v[230:231]
	s_waitcnt vmcnt(8)
	v_pk_add_f32 v[88:89], v[88:89], v[232:233]
	v_pk_add_f32 v[90:91], v[90:91], v[234:235]
	s_waitcnt vmcnt(7)
	v_pk_add_f32 v[110:111], v[110:111], v[120:121]
	v_pk_add_f32 v[112:113], v[112:113], v[122:123]
	s_waitcnt vmcnt(6)
	v_pk_add_f32 v[106:107], v[106:107], v[124:125]
	v_pk_add_f32 v[108:109], v[108:109], v[126:127]
	s_waitcnt vmcnt(5)
	v_pk_add_f32 v[102:103], v[102:103], v[128:129]
	v_pk_add_f32 v[104:105], v[104:105], v[130:131]
	s_waitcnt vmcnt(4)
	v_pk_add_f32 v[98:99], v[98:99], v[132:133]
	v_pk_add_f32 v[100:101], v[100:101], v[134:135]
	s_waitcnt vmcnt(3)
	v_pk_add_f32 v[92:93], v[92:93], v[136:137]
	v_pk_add_f32 v[94:95], v[94:95], v[138:139]
	s_waitcnt vmcnt(2)
	v_pk_add_f32 v[84:85], v[84:85], v[140:141]
	v_pk_add_f32 v[86:87], v[86:87], v[142:143]
	s_waitcnt vmcnt(1)
	v_pk_add_f32 v[80:81], v[80:81], v[144:145]
	v_pk_add_f32 v[82:83], v[82:83], v[146:147]
	s_waitcnt vmcnt(0) lgkmcnt(0)
	v_pk_add_f32 v[88:89], v[88:89], v[152:153]
	v_pk_add_f32 v[90:91], v[90:91], v[154:155]
	s_mov_b32 s18, 0x2c0000
	v_mul_f32_e32 v67, v111, v111
	v_mul_f32_e32 v71, v107, v107
	v_fmac_f32_e32 v67, v110, v110
	v_fmac_f32_e32 v71, v106, v106
	v_fmac_f32_e32 v67, v112, v112
	v_fmac_f32_e32 v71, v108, v108
	v_fmac_f32_e32 v67, v113, v113
	v_fmac_f32_e32 v71, v109, v109
	v_add_f32_e32 v67, v67, v71
	v_mul_f32_e32 v71, v103, v103
	v_fmac_f32_e32 v71, v102, v102
	v_fmac_f32_e32 v71, v104, v104
	v_fmac_f32_e32 v71, v105, v105
	v_add_f32_e32 v67, v67, v71
	v_mul_f32_e32 v71, v99, v99
	v_mov_b32_e32 v114, v93
	v_mov_b32_e32 v115, v85
	v_fmac_f32_e32 v71, v98, v98
	v_mov_b32_e32 v96, v92
	v_mov_b32_e32 v97, v84
	v_pk_mul_f32 v[114:115], v[114:115], v[114:115]
	v_fmac_f32_e32 v71, v100, v100
	v_pk_fma_f32 v[96:97], v[96:97], v[96:97], v[114:115]
	v_mov_b32_e32 v114, v94
	v_mov_b32_e32 v115, v86
	v_fmac_f32_e32 v71, v101, v101
	v_pk_fma_f32 v[96:97], v[114:115], v[114:115], v[96:97]
	v_mov_b32_e32 v114, v95
	v_mov_b32_e32 v115, v87
	v_add_f32_e32 v67, v67, v71
	v_pk_fma_f32 v[96:97], v[114:115], v[114:115], v[96:97]
	v_mov_b32_e32 v114, v81
	v_add_f32_e32 v67, v67, v96
	v_mov_b32_e32 v115, v89
	v_add_f32_e32 v67, v67, v97
	v_mov_b32_e32 v96, v80
	v_mov_b32_e32 v97, v88
	v_pk_mul_f32 v[114:115], v[114:115], v[114:115]
	s_nop 0
	v_pk_fma_f32 v[96:97], v[96:97], v[96:97], v[114:115]
	v_mov_b32_e32 v114, v82
	v_mov_b32_e32 v115, v90
	v_pk_fma_f32 v[96:97], v[114:115], v[114:115], v[96:97]
	v_mov_b32_e32 v114, v83
	v_mov_b32_e32 v115, v91
	v_pk_fma_f32 v[96:97], v[114:115], v[114:115], v[96:97]
	s_nop 0
	v_add_f32_e32 v67, v67, v96
	v_add_f32_e32 v71, v67, v97
	v_and_b32_e32 v67, 64, v215
	v_add_u32_e32 v115, 64, v67
	v_xor_b32_e32 v67, 32, v215
	v_cmp_lt_i32_e32 vcc, v67, v115
	s_nop 1
	v_cndmask_b32_e32 v67, v215, v67, vcc
	v_lshlrev_b32_e32 v67, 2, v67
	ds_bpermute_b32 v96, v67, v71
	s_waitcnt lgkmcnt(0)
	v_add_f32_e32 v96, v71, v96
	v_xor_b32_e32 v71, 16, v215
	v_cmp_lt_i32_e32 vcc, v71, v115
	s_nop 1
	v_cndmask_b32_e32 v71, v215, v71, vcc
	v_lshlrev_b32_e32 v71, 2, v71
	ds_bpermute_b32 v97, v71, v96
	s_waitcnt lgkmcnt(0)
	v_add_f32_e32 v97, v96, v97
	v_xor_b32_e32 v96, 8, v215
	v_cmp_lt_i32_e32 vcc, v96, v115
	s_nop 1
	v_cndmask_b32_e32 v96, v215, v96, vcc
	v_lshlrev_b32_e32 v96, 2, v96
	ds_bpermute_b32 v114, v96, v97
	s_waitcnt lgkmcnt(0)
	v_add_f32_e32 v114, v97, v114
	v_xor_b32_e32 v97, 4, v215
	v_cmp_lt_i32_e32 vcc, v97, v115
	s_nop 1
	v_cndmask_b32_e32 v97, v215, v97, vcc
	v_lshlrev_b32_e32 v97, 2, v97
	ds_bpermute_b32 v117, v97, v114
	s_waitcnt lgkmcnt(0)
	v_add_f32_e32 v117, v114, v117
	v_xor_b32_e32 v114, 2, v215
	v_cmp_lt_i32_e32 vcc, v114, v115
	s_nop 1
	v_cndmask_b32_e32 v114, v215, v114, vcc
	v_lshlrev_b32_e32 v114, 2, v114
	ds_bpermute_b32 v118, v114, v117
	s_waitcnt lgkmcnt(0)
	v_add_f32_e32 v117, v117, v118
	v_xor_b32_e32 v118, 1, v215
	v_cmp_lt_i32_e32 vcc, v118, v115
	s_nop 1
	v_cndmask_b32_e32 v115, v215, v118, vcc
	v_lshlrev_b32_e32 v115, 2, v115
	ds_bpermute_b32 v118, v115, v117
	s_andn2_b64 vcc, exec, s[8:9]
	s_cbranch_vccnz .LBB0_308
	s_waitcnt lgkmcnt(0)
	v_add_f32_e32 v117, v117, v118
	v_fmamk_f32 v117, v117, 0x3a000000, v212
	s_mov_b32 s3, 0x800000
	v_mul_f32_e32 v118, 0x4b800000, v117
	v_cmp_gt_f32_e32 vcc, s3, v117
	v_lshlrev_b32_e32 v66, 1, v66
	s_mov_b64 s[6:7], 0x1cc00000
	v_cndmask_b32_e32 v117, v117, v118, vcc
	v_rsq_f32_e32 v117, v117
	s_nop 0
	v_mul_f32_e32 v118, 0x45800000, v117
	v_cndmask_b32_e32 v118, v117, v118, vcc
	v_pk_mul_f32 v[110:111], v[110:111], v[118:119] op_sel_hi:[1,0]
	v_pk_mul_f32 v[106:107], v[106:107], v[118:119] op_sel_hi:[1,0]
	v_pk_fma_f32 v[62:63], v[2:3], v[110:111], v[62:63]
	v_pk_fma_f32 v[58:59], v[6:7], v[106:107], v[58:59]
	v_pk_mul_f32 v[102:103], v[102:103], v[118:119] op_sel_hi:[1,0]
	v_pk_mul_f32 v[112:113], v[112:113], v[118:119] op_sel_hi:[1,0]
	v_pk_mul_f32 v[108:109], v[108:109], v[118:119] op_sel_hi:[1,0]
	v_mul_f32_e32 v106, v63, v63
	v_pk_fma_f32 v[54:55], v[10:11], v[102:103], v[54:55]
	v_mul_f32_e32 v102, v59, v59
	v_pk_mul_f32 v[98:99], v[98:99], v[118:119] op_sel_hi:[1,0]
	v_pk_mul_f32 v[92:93], v[92:93], v[118:119] op_sel_hi:[1,0]
	v_pk_mul_f32 v[84:85], v[84:85], v[118:119] op_sel_hi:[1,0]
	v_pk_fma_f32 v[64:65], v[4:5], v[112:113], v[64:65]
	v_pk_fma_f32 v[60:61], v[8:9], v[108:109], v[60:61]
	v_fmac_f32_e32 v106, v62, v62
	v_pk_mul_f32 v[104:105], v[104:105], v[118:119] op_sel_hi:[1,0]
	v_fmac_f32_e32 v102, v58, v58
	v_pk_fma_f32 v[50:51], v[14:15], v[98:99], v[50:51]
	v_mul_f32_e32 v98, v55, v55
	v_pk_fma_f32 v[46:47], v[18:19], v[92:93], v[46:47]
	v_pk_mul_f32 v[86:87], v[86:87], v[118:119] op_sel_hi:[1,0]
	v_pk_fma_f32 v[42:43], v[22:23], v[84:85], v[42:43]
	v_fmac_f32_e32 v106, v64, v64
	v_pk_fma_f32 v[56:57], v[12:13], v[104:105], v[56:57]
	v_fmac_f32_e32 v102, v60, v60
	v_pk_mul_f32 v[100:101], v[100:101], v[118:119] op_sel_hi:[1,0]
	v_fmac_f32_e32 v98, v54, v54
	v_pk_mul_f32 v[94:95], v[94:95], v[118:119] op_sel_hi:[1,0]
	v_mul_f32_e32 v92, v51, v51
	v_pk_fma_f32 v[44:45], v[24:25], v[86:87], v[44:45]
	v_mov_b32_e32 v86, v43
	v_mov_b32_e32 v87, v47
	v_fmac_f32_e32 v106, v65, v65
	v_fmac_f32_e32 v102, v61, v61
	v_pk_fma_f32 v[52:53], v[16:17], v[100:101], v[52:53]
	v_fmac_f32_e32 v98, v56, v56
	v_pk_fma_f32 v[48:49], v[20:21], v[94:95], v[48:49]
	v_fmac_f32_e32 v92, v50, v50
	v_pk_mul_f32 v[82:83], v[82:83], v[118:119] op_sel_hi:[1,0]
	v_mov_b32_e32 v84, v42
	v_mov_b32_e32 v85, v46
	v_pk_mul_f32 v[86:87], v[86:87], v[86:87]
	v_add_f32_e32 v102, v106, v102
	v_fmac_f32_e32 v98, v57, v57
	v_fmac_f32_e32 v92, v52, v52
	v_pk_mul_f32 v[80:81], v[80:81], v[118:119] op_sel_hi:[1,0]
	v_pk_fma_f32 v[40:41], v[28:29], v[82:83], v[40:41]
	v_mov_b32_e32 v82, v44
	v_mov_b32_e32 v83, v48
	v_pk_fma_f32 v[84:85], v[84:85], v[84:85], v[86:87]
	v_add_f32_e32 v98, v98, v102
	v_fmac_f32_e32 v92, v53, v53
	v_pk_fma_f32 v[38:39], v[26:27], v[80:81], v[38:39]
	v_mov_b32_e32 v80, v45
	v_mov_b32_e32 v81, v49
	v_pk_fma_f32 v[82:83], v[82:83], v[82:83], v[84:85]
	v_add_f32_e32 v92, v92, v98
	v_pk_fma_f32 v[80:81], v[80:81], v[80:81], v[82:83]
	v_pk_mul_f32 v[82:83], v[88:89], v[118:119] op_sel_hi:[1,0]
	v_add_f32_e32 v81, v81, v92
	v_pk_fma_f32 v[34:35], v[30:31], v[82:83], v[34:35]
	v_add_f32_e32 v92, v80, v81
	v_pk_mul_f32 v[80:81], v[90:91], v[118:119] op_sel_hi:[1,0]
	v_mov_b32_e32 v86, v35
	v_mov_b32_e32 v87, v39
	v_pk_fma_f32 v[36:37], v[32:33], v[80:81], v[36:37]
	v_mov_b32_e32 v84, v34
	v_mov_b32_e32 v85, v38
	v_pk_mul_f32 v[86:87], v[86:87], v[86:87]
	v_mov_b32_e32 v82, v36
	v_mov_b32_e32 v83, v40
	v_pk_fma_f32 v[84:85], v[84:85], v[84:85], v[86:87]
	v_mov_b32_e32 v80, v37
	v_mov_b32_e32 v81, v41
	v_pk_fma_f32 v[82:83], v[82:83], v[82:83], v[84:85]
	global_store_dwordx4 v[68:69], v[62:65], off
	v_pk_fma_f32 v[80:81], v[80:81], v[80:81], v[82:83]
	global_store_dwordx4 v[68:69], v[58:61], off offset:1024
	global_store_dwordx4 v[68:69], v[54:57], off offset:2048
	global_store_dwordx4 v[68:69], v[50:53], off offset:3072
	global_store_dwordx4 v[78:79], v[46:49], off
	v_add_f32_e32 v81, v81, v92
	v_add_f32_e32 v80, v80, v81
	ds_bpermute_b32 v67, v67, v80
	v_mov_b32_e32 v69, v1
	global_store_dwordx4 v[72:73], v[42:45], off
	global_store_dwordx4 v[74:75], v[38:41], off
	global_store_dwordx4 v[76:77], v[34:37], off
	s_waitcnt lgkmcnt(0)
	v_add_f32_e32 v67, v80, v67
	ds_bpermute_b32 v71, v71, v67
	s_waitcnt lgkmcnt(0)
	v_add_f32_e32 v67, v67, v71
	ds_bpermute_b32 v71, v96, v67
	s_waitcnt lgkmcnt(0)
	v_add_f32_e32 v67, v67, v71
	ds_bpermute_b32 v71, v97, v67
	s_waitcnt lgkmcnt(0)
	v_add_f32_e32 v67, v67, v71
	ds_bpermute_b32 v71, v114, v67
	s_waitcnt lgkmcnt(0)
	v_add_f32_e32 v67, v67, v71
	ds_bpermute_b32 v71, v115, v67
	s_waitcnt lgkmcnt(0)
	v_add_f32_e32 v67, v67, v71
	v_fmamk_f32 v67, v67, 0x3a000000, v212
	v_mul_f32_e32 v68, 0x4b800000, v67
	v_cmp_gt_f32_e32 vcc, s3, v67
	s_mov_b32 s3, 0x1cc00000
	s_nop 0
	v_cndmask_b32_e32 v67, v67, v68, vcc
	v_rsq_f32_e32 v67, v67
	s_nop 0
	v_mul_f32_e32 v68, 0x45800000, v67
	v_cndmask_b32_e32 v71, v67, v68, vcc
	v_mov_b32_e32 v67, v1
	v_lshl_add_u64 v[66:67], s[34:35], 0, v[66:67]
	v_lshlrev_b32_e32 v68, 1, v116
	v_mul_f32_e32 v62, v62, v71
	v_mul_f32_e32 v63, v63, v71
	v_lshl_add_u64 v[66:67], v[66:67], 0, v[68:69]
	v_cvt_pk_bf16_f32 v62, v62, v63
	v_mul_f32_e32 v63, v64, v71
	v_mul_f32_e32 v64, v65, v71
	v_cvt_pk_bf16_f32 v63, v63, v64
	v_add_co_u32_e32 v64, vcc, s3, v66
	v_mul_f32_e32 v58, v58, v71
	s_nop 0
	v_addc_co_u32_e32 v65, vcc, 0, v67, vcc
	v_mul_f32_e32 v59, v59, v71
	v_lshl_add_u64 v[68:69], v[66:67], 0, s[6:7]
	global_store_dwordx2 v[64:65], v[62:63], off
	v_cvt_pk_bf16_f32 v58, v58, v59
	v_mul_f32_e32 v59, v60, v71
	v_mul_f32_e32 v54, v54, v71
	v_mul_f32_e32 v55, v55, v71
	v_mul_f32_e32 v60, v61, v71
	v_cvt_pk_bf16_f32 v59, v59, v60
	global_store_dwordx2 v[68:69], v[58:59], off offset:512
	v_cvt_pk_bf16_f32 v54, v54, v55
	v_mul_f32_e32 v55, v56, v71
	v_mul_f32_e32 v50, v50, v71
	v_mul_f32_e32 v51, v51, v71
	v_mul_f32_e32 v56, v57, v71
	v_cvt_pk_bf16_f32 v55, v55, v56
	global_store_dwordx2 v[68:69], v[54:55], off offset:1024
	v_cvt_pk_bf16_f32 v50, v50, v51
	v_mul_f32_e32 v51, v52, v71
	v_mul_f32_e32 v46, v46, v71
	v_mul_f32_e32 v47, v47, v71
	v_mul_f32_e32 v52, v53, v71
	v_cvt_pk_bf16_f32 v51, v51, v52
	global_store_dwordx2 v[68:69], v[50:51], off offset:1536
	v_cvt_pk_bf16_f32 v46, v46, v47
	v_mul_f32_e32 v47, v48, v71
	v_mul_f32_e32 v42, v42, v71
	v_mul_f32_e32 v43, v43, v71
	v_mul_f32_e32 v48, v49, v71
	v_cvt_pk_bf16_f32 v47, v47, v48
	global_store_dwordx2 v[68:69], v[46:47], off offset:2048
	v_cvt_pk_bf16_f32 v42, v42, v43
	v_mul_f32_e32 v43, v44, v71
	v_mul_f32_e32 v38, v38, v71
	v_mul_f32_e32 v39, v39, v71
	v_mul_f32_e32 v44, v45, v71
	v_cvt_pk_bf16_f32 v43, v43, v44
	global_store_dwordx2 v[68:69], v[42:43], off offset:2560
	v_cvt_pk_bf16_f32 v38, v38, v39
	v_mul_f32_e32 v39, v40, v71
	v_mul_f32_e32 v34, v34, v71
	v_mul_f32_e32 v35, v35, v71
	v_mul_f32_e32 v40, v41, v71
	v_cvt_pk_bf16_f32 v39, v39, v40
	global_store_dwordx2 v[68:69], v[38:39], off offset:3072
	v_cvt_pk_bf16_f32 v34, v34, v35
	v_mul_f32_e32 v35, v36, v71
	v_mul_f32_e32 v36, v37, v71
	v_cvt_pk_bf16_f32 v35, v35, v36
	global_store_dwordx2 v[68:69], v[34:35], off offset:3584

; __device__ __forceinline__ int opaque_tid() { int t = threadIdx.x; asm volatile("" : "+v"(t)); return t; }
; __device__ __forceinline__ void phase_resid(const Params& p, const float* g, bool first, bool last, int nsplit) {
;     const int tid = opaque_tid(), lane = tid & 63, gw = (blockIdx.x * NTHREADS + tid) >> 6, nw = (gridDim.x * NTHREADS) >> 6;
;     float* h = (float*)(p.ws + WS_H); bf16_t* abf = (bf16_t*)(p.ws + WS_ABF);
;     const bf16_t* mix = (const bf16_t*)(p.ws + WS_MIX);
;     const float* part = (const float*)(p.ws + WS_PART);
;     f32x4 gv[8];
; #pragma unroll
;     for (int i = 0; i < 8; ++i) gv[i] = *(const f32x4*)(g + lane * 4 + 256 * i);
;     ...
;     if (gw < 16) {
;         const int row = PADR + gw;
;         f32x4 mv[8], hv[8];
; #pragma unroll
;         for (int i = 0; i < 8; ++i) { mv[i] = (f32x4){0.f, 0.f, 0.f, 0.f}; hv[i] = *(const f32x4*)(HROW(row) + lane * 4 + 256 * i); }
;         for (int sp = 0; sp < nsplit; ++sp) {
; #pragma unroll
;             for (int i = 0; i < 8; ++i) mv[i] += *(const f32x4*)(part + (size_t)(sp * 16 + gw) * DM + lane * 4 + 256 * i);
.LBB0_763:
	s_andn2_b64 vcc, exec, s[4:5]
	s_cbranch_vccnz .LBB0_1567
	v_readlane_b32 s0, v254, 56
	s_cmp_lt_i32 s0, 3
	s_mov_b64 s[0:1], -1
	s_cbranch_scc1 .LBB0_806
	v_readlane_b32 s0, v254, 56
	s_cmp_gt_i32 s0, 3
	s_mov_b64 s[0:1], -1
	s_cbranch_scc0 .LBB0_778
	s_lshl_b32 s0, s90, 11
	s_ashr_i32 s1, s0, 31
	v_mov_b32_e32 v0, v210
	s_lshl_b64 s[0:1], s[0:1], 2
	s_add_u32 s0, s46, s0
	s_waitcnt vmcnt(0)
	v_lshlrev_b32_e32 v2, 2, v0
	v_and_b32_e32 v110, 0xfc, v2
	s_addc_u32 s1, s13, s1
	v_lshlrev_b32_e32 v98, 2, v110
	v_mov_b32_e32 v99, v1
	v_lshl_add_u64 v[18:19], s[0:1], 0, v[98:99]
	v_add_co_u32_e32 v30, vcc, 0x1000, v18
	global_load_dwordx4 v[2:5], v98, s[0:1]
	global_load_dwordx4 v[6:9], v98, s[0:1] offset:1024
	global_load_dwordx4 v[10:13], v98, s[0:1] offset:2048
	global_load_dwordx4 v[14:17], v98, s[0:1] offset:3072
	v_addc_co_u32_e32 v31, vcc, 0, v19, vcc
	global_load_dwordx4 v[18:21], v[30:31], off
	global_load_dwordx4 v[22:25], v[30:31], off offset:1024
	global_load_dwordx4 v[26:29], v[30:31], off offset:2048
	s_nop 0
	global_load_dwordx4 v[30:33], v[30:31], off offset:3072
	s_add_i32 s0, s31, 7
	s_cmp_lt_u32 s0, 17
	v_readlane_b32 s2, v252, 5
	s_cselect_b64 s[0:1], -1, 0
	s_add_u32 s8, s34, 0x18a00000
	v_add_u32_e32 v34, s2, v0
	s_movk_i32 s2, 0x400
	s_addc_u32 s9, s35, 0
	v_lshrrev_b32_e32 v66, 6, v34
	v_cmp_gt_u32_e32 vcc, 64, v0
	s_cmp_lt_u32 s80, 16
	s_cselect_b64 s[100:101], -1, 0
	s_and_b64 vcc, vcc, s[100:101]
	v_mov_b32_e32 v250, s80
	v_mov_b32_e32 v251, 0
	v_and_b32_e32 v140, 63, v0
	s_and_saveexec_b64 s[4:5], vcc
	s_cbranch_execz .LBB0_770
	v_lshlrev_b32_e32 v34, 11, v250
	v_or_b32_e32 v0, 0x78000, v34
	v_mov_b32_e32 v35, v1
	v_lshl_add_u64 v[68:69], v[0:1], 2, s[8:9]
	v_lshl_add_u64 v[34:35], v[34:35], 2, s[40:41]
	v_cndmask_b32_e64 v35, v69, v35, s[0:1]
	v_cndmask_b32_e64 v34, v68, v34, s[0:1]
	v_lshl_add_u64 v[34:35], v[34:35], 0, v[98:99]
	s_movk_i32 s2, 0x1000
	global_load_dwordx4 v[62:65], v[34:35], off
	global_load_dwordx4 v[58:61], v[34:35], off offset:1024
	global_load_dwordx4 v[54:57], v[34:35], off offset:2048
	global_load_dwordx4 v[50:53], v[34:35], off offset:3072
	v_add_co_u32_e32 v34, vcc, s2, v34
	v_mov_b32_e32 v67, v1
	s_nop 0
	v_addc_co_u32_e32 v35, vcc, 0, v35, vcc
	global_load_dwordx4 v[46:49], v[34:35], off
	global_load_dwordx4 v[42:45], v[34:35], off offset:1024
	global_load_dwordx4 v[38:41], v[34:35], off offset:2048
	s_nop 0
	global_load_dwordx4 v[34:37], v[34:35], off offset:3072
	v_lshlrev_b64 v[70:71], 13, v[250:251]
	v_lshl_or_b32 v70, v140, 4, v70
	v_mov_b32_e32 v102, 0
	v_lshl_add_u64 v[70:71], s[34:35], 0, v[70:71]
	s_mov_b64 s[10:11], 0
	v_mov_b32_e32 v103, v102
	v_mov_b32_e32 v104, v102
	v_mov_b32_e32 v105, v102
	v_mov_b32_e32 v72, v102
	v_mov_b32_e32 v73, v102
	v_mov_b32_e32 v74, v102
	v_mov_b32_e32 v75, v102
	v_mov_b32_e32 v76, v102
	v_mov_b32_e32 v77, v102
	v_mov_b32_e32 v78, v102
	v_mov_b32_e32 v79, v102
	v_mov_b32_e32 v80, v102
	v_mov_b32_e32 v81, v102
	v_mov_b32_e32 v82, v102
	v_mov_b32_e32 v83, v102
	v_mov_b32_e32 v88, v102
	v_mov_b32_e32 v89, v102
	v_mov_b32_e32 v84, v102
	v_mov_b32_e32 v85, v102
	v_mov_b32_e32 v90, v102
	v_mov_b32_e32 v91, v102
	v_mov_b32_e32 v86, v102
	v_mov_b32_e32 v87, v102
	v_mov_b32_e32 v94, v102
	v_mov_b32_e32 v95, v102
	v_mov_b32_e32 v92, v102
	v_mov_b32_e32 v93, v102
	v_mov_b32_e32 v100, v102
	v_mov_b32_e32 v101, v102
	v_mov_b32_e32 v96, v102
	v_mov_b32_e32 v97, v102
	s_mov_b32 s3, 0x415c8000
	s_mov_b32 s6, 0x415c9000
	s_mov_b32 s7, 0x415ca000
	s_mov_b32 s12, 0x415e8000
	s_mov_b32 s13, 0x415e9000
	s_mov_b32 s14, 0x415ea000
	v_subrev_u32_e32 v141, s34, v70
	v_add_u32_e32 v142, 0x1000, v141
	v_add_u32_e32 v143, 0x2000, v141
	s_add_u32 s100, s34, 0x415c8000
	s_addc_u32 s101, s35, 0
	global_load_dwordx4 v[112:115], v141, s[100:101] offset:1280
	global_load_dwordx4 v[116:119], v141, s[100:101] offset:2304
	global_load_dwordx4 v[120:123], v141, s[100:101] offset:3328
	global_load_dwordx4 v[124:127], v142, s[100:101] offset:256
	global_load_dwordx4 v[128:131], v142, s[100:101] offset:1280
	global_load_dwordx4 v[132:135], v142, s[100:101] offset:2304
	global_load_dwordx4 v[136:139], v142, s[100:101] offset:3328
	global_load_dwordx4 v[144:147], v143, s[100:101] offset:256
	s_add_u32 s100, s100, 0x20000
	s_addc_u32 s101, s101, 0
	global_load_dwordx4 v[148:151], v141, s[100:101] offset:1280
	global_load_dwordx4 v[152:155], v141, s[100:101] offset:2304
	global_load_dwordx4 v[156:159], v141, s[100:101] offset:3328
	global_load_dwordx4 v[160:163], v142, s[100:101] offset:256
	global_load_dwordx4 v[164:167], v142, s[100:101] offset:1280
	global_load_dwordx4 v[168:171], v142, s[100:101] offset:2304
	global_load_dwordx4 v[172:175], v142, s[100:101] offset:3328
	global_load_dwordx4 v[176:179], v143, s[100:101] offset:256
	s_add_u32 s100, s100, 0x20000
	s_addc_u32 s101, s101, 0
	global_load_dwordx4 v[180:183], v141, s[100:101] offset:1280
	global_load_dwordx4 v[184:187], v141, s[100:101] offset:2304
	global_load_dwordx4 v[188:191], v141, s[100:101] offset:3328
	global_load_dwordx4 v[192:195], v142, s[100:101] offset:256
	global_load_dwordx4 v[196:199], v142, s[100:101] offset:1280
	global_load_dwordx4 v[200:203], v142, s[100:101] offset:2304
	global_load_dwordx4 v[204:207], v142, s[100:101] offset:3328
	global_load_dwordx4 v[224:227], v143, s[100:101] offset:256
	s_add_u32 s100, s100, 0x20000
	s_addc_u32 s101, s101, 0
	s_waitcnt vmcnt(23)
	v_pk_add_f32 v[100:101], v[100:101], v[112:113]
	v_pk_add_f32 v[96:97], v[96:97], v[114:115]
	global_load_dwordx4 v[112:115], v141, s[100:101] offset:1280
	s_waitcnt vmcnt(23)
; __device__ __forceinline__ void phase_resid(const Params& p, const float* g, bool first, bool last, int nsplit) {
;     ...
;         for (int sp = 0; sp < nsplit; ++sp) {
; #pragma unroll
;             for (int i = 0; i < 8; ++i) mv[i] += *(const f32x4*)(part + (size_t)(sp * 16 + gw) * DM + lane * 4 + 256 * i);
;         }
	v_pk_add_f32 v[94:95], v[94:95], v[116:117]
	v_pk_add_f32 v[92:93], v[92:93], v[118:119]
	global_load_dwordx4 v[116:119], v141, s[100:101] offset:2304
	s_waitcnt vmcnt(23)
	v_pk_add_f32 v[90:91], v[90:91], v[120:121]
	v_pk_add_f32 v[86:87], v[86:87], v[122:123]
	global_load_dwordx4 v[120:123], v141, s[100:101] offset:3328
	s_waitcnt vmcnt(23)
	v_pk_add_f32 v[88:89], v[88:89], v[124:125]
	v_pk_add_f32 v[84:85], v[84:85], v[126:127]
	global_load_dwordx4 v[124:127], v142, s[100:101] offset:256
	s_waitcnt vmcnt(23)
	v_pk_add_f32 v[80:81], v[80:81], v[128:129]
	v_pk_add_f32 v[82:83], v[82:83], v[130:131]
	global_load_dwordx4 v[128:131], v142, s[100:101] offset:1280
	s_waitcnt vmcnt(23)
	v_pk_add_f32 v[76:77], v[76:77], v[132:133]
	v_pk_add_f32 v[78:79], v[78:79], v[134:135]
	global_load_dwordx4 v[132:135], v142, s[100:101] offset:2304
	s_waitcnt vmcnt(23)
	v_pk_add_f32 v[72:73], v[72:73], v[136:137]
	v_pk_add_f32 v[74:75], v[74:75], v[138:139]
	global_load_dwordx4 v[136:139], v142, s[100:101] offset:3328
	s_waitcnt vmcnt(23)
	v_pk_add_f32 v[102:103], v[102:103], v[144:145]
	v_pk_add_f32 v[104:105], v[104:105], v[146:147]
	global_load_dwordx4 v[144:147], v143, s[100:101] offset:256
	s_add_u32 s100, s100, 0x20000
	s_addc_u32 s101, s101, 0
	s_waitcnt vmcnt(23)
	v_pk_add_f32 v[100:101], v[100:101], v[148:149]
	v_pk_add_f32 v[96:97], v[96:97], v[150:151]
	global_load_dwordx4 v[148:151], v141, s[100:101] offset:1280
	s_waitcnt vmcnt(23)
	v_pk_add_f32 v[94:95], v[94:95], v[152:153]
	v_pk_add_f32 v[92:93], v[92:93], v[154:155]
	global_load_dwordx4 v[152:155], v141, s[100:101] offset:2304
	s_waitcnt vmcnt(23)
	v_pk_add_f32 v[90:91], v[90:91], v[156:157]
	v_pk_add_f32 v[86:87], v[86:87], v[158:159]
	global_load_dwordx4 v[156:159], v141, s[100:101] offset:3328
	s_waitcnt vmcnt(23)
	v_pk_add_f32 v[88:89], v[88:89], v[160:161]
	v_pk_add_f32 v[84:85], v[84:85], v[162:163]
	global_load_dwordx4 v[160:163], v142, s[100:101] offset:256
	s_waitcnt vmcnt(23)
	v_pk_add_f32 v[80:81], v[80:81], v[164:165]
	v_pk_add_f32 v[82:83], v[82:83], v[166:167]
	global_load_dwordx4 v[164:167], v142, s[100:101] offset:1280
	s_waitcnt vmcnt(23)
	v_pk_add_f32 v[76:77], v[76:77], v[168:169]
	v_pk_add_f32 v[78:79], v[78:79], v[170:171]
	global_load_dwordx4 v[168:171], v142, s[100:101] offset:2304
	s_waitcnt vmcnt(23)
	v_pk_add_f32 v[72:73], v[72:73], v[172:173]
	v_pk_add_f32 v[74:75], v[74:75], v[174:175]
	global_load_dwordx4 v[172:175], v142, s[100:101] offset:3328
	s_waitcnt vmcnt(23)
	v_pk_add_f32 v[102:103], v[102:103], v[176:177]
	v_pk_add_f32 v[104:105], v[104:105], v[178:179]
	global_load_dwordx4 v[176:179], v143, s[100:101] offset:256
	s_add_u32 s100, s100, 0x20000
	s_addc_u32 s101, s101, 0
	s_waitcnt vmcnt(23)
	v_pk_add_f32 v[100:101], v[100:101], v[180:181]
	v_pk_add_f32 v[96:97], v[96:97], v[182:183]
	global_load_dwordx4 v[180:183], v141, s[100:101] offset:1280
	s_waitcnt vmcnt(23)
	v_pk_add_f32 v[94:95], v[94:95], v[184:185]
	v_pk_add_f32 v[92:93], v[92:93], v[186:187]
	global_load_dwordx4 v[184:187], v141, s[100:101] offset:2304
	s_waitcnt vmcnt(23)
	v_pk_add_f32 v[90:91], v[90:91], v[188:189]
	v_pk_add_f32 v[86:87], v[86:87], v[190:191]
	global_load_dwordx4 v[188:191], v141, s[100:101] offset:3328
	s_waitcnt vmcnt(23)
	v_pk_add_f32 v[88:89], v[88:89], v[192:193]
	v_pk_add_f32 v[84:85], v[84:85], v[194:195]
	global_load_dwordx4 v[192:195], v142, s[100:101] offset:256
	s_waitcnt vmcnt(23)
	v_pk_add_f32 v[80:81], v[80:81], v[196:197]
	v_pk_add_f32 v[82:83], v[82:83], v[198:199]
	global_load_dwordx4 v[196:199], v142, s[100:101] offset:1280
	s_waitcnt vmcnt(23)
	v_pk_add_f32 v[76:77], v[76:77], v[200:201]
	v_pk_add_f32 v[78:79], v[78:79], v[202:203]
	global_load_dwordx4 v[200:203], v142, s[100:101] offset:2304
	s_waitcnt vmcnt(23)
	v_pk_add_f32 v[72:73], v[72:73], v[204:205]
	v_pk_add_f32 v[74:75], v[74:75], v[206:207]
	global_load_dwordx4 v[204:207], v142, s[100:101] offset:3328
	s_waitcnt vmcnt(23)
	v_pk_add_f32 v[102:103], v[102:103], v[224:225]
	v_pk_add_f32 v[104:105], v[104:105], v[226:227]
	global_load_dwordx4 v[224:227], v143, s[100:101] offset:256
	s_add_u32 s100, s100, 0x20000
	s_addc_u32 s101, s101, 0
	s_waitcnt vmcnt(23)
	v_pk_add_f32 v[100:101], v[100:101], v[112:113]
	v_pk_add_f32 v[96:97], v[96:97], v[114:115]
	global_load_dwordx4 v[112:115], v141, s[100:101] offset:1280
	s_waitcnt vmcnt(23)
	v_pk_add_f32 v[94:95], v[94:95], v[116:117]
	v_pk_add_f32 v[92:93], v[92:93], v[118:119]
	global_load_dwordx4 v[116:119], v141, s[100:101] offset:2304
	s_waitcnt vmcnt(23)
	v_pk_add_f32 v[90:91], v[90:91], v[120:121]
	v_pk_add_f32 v[86:87], v[86:87], v[122:123]
	global_load_dwordx4 v[120:123], v141, s[100:101] offset:3328
	s_waitcnt vmcnt(23)
	v_pk_add_f32 v[88:89], v[88:89], v[124:125]
	v_pk_add_f32 v[84:85], v[84:85], v[126:127]
	global_load_dwordx4 v[124:127], v142, s[100:101] offset:256
	s_waitcnt vmcnt(23)
	v_pk_add_f32 v[80:81], v[80:81], v[128:129]
	v_pk_add_f32 v[82:83], v[82:83], v[130:131]
	global_load_dwordx4 v[128:131], v142, s[100:101] offset:1280
	s_waitcnt vmcnt(23)
	v_pk_add_f32 v[76:77], v[76:77], v[132:133]
	v_pk_add_f32 v[78:79], v[78:79], v[134:135]
	global_load_dwordx4 v[132:135], v142, s[100:101] offset:2304
	s_waitcnt vmcnt(23)
	v_pk_add_f32 v[72:73], v[72:73], v[136:137]
	v_pk_add_f32 v[74:75], v[74:75], v[138:139]
	global_load_dwordx4 v[136:139], v142, s[100:101] offset:3328
	s_waitcnt vmcnt(23)
	v_pk_add_f32 v[102:103], v[102:103], v[144:145]
	v_pk_add_f32 v[104:105], v[104:105], v[146:147]
	global_load_dwordx4 v[144:147], v143, s[100:101] offset:256
	s_add_u32 s100, s100, 0x20000
	s_addc_u32 s101, s101, 0
	s_waitcnt vmcnt(23)
; __device__ __forceinline__ void phase_resid(const Params& p, const float* g, bool first, bool last, int nsplit) {
;     ...
;         for (int sp = 0; sp < nsplit; ++sp) {
; #pragma unroll
;             for (int i = 0; i < 8; ++i) mv[i] += *(const f32x4*)(part + (size_t)(sp * 16 + gw) * DM + lane * 4 + 256 * i);
;         }
	v_pk_add_f32 v[100:101], v[100:101], v[148:149]
	v_pk_add_f32 v[96:97], v[96:97], v[150:151]
	global_load_dwordx4 v[148:151], v141, s[100:101] offset:1280
	s_waitcnt vmcnt(23)
	v_pk_add_f32 v[94:95], v[94:95], v[152:153]
	v_pk_add_f32 v[92:93], v[92:93], v[154:155]
	global_load_dwordx4 v[152:155], v141, s[100:101] offset:2304
	s_waitcnt vmcnt(23)
	v_pk_add_f32 v[90:91], v[90:91], v[156:157]
	v_pk_add_f32 v[86:87], v[86:87], v[158:159]
	global_load_dwordx4 v[156:159], v141, s[100:101] offset:3328
	s_waitcnt vmcnt(23)
	v_pk_add_f32 v[88:89], v[88:89], v[160:161]
	v_pk_add_f32 v[84:85], v[84:85], v[162:163]
	global_load_dwordx4 v[160:163], v142, s[100:101] offset:256
	s_waitcnt vmcnt(23)
	v_pk_add_f32 v[80:81], v[80:81], v[164:165]
	v_pk_add_f32 v[82:83], v[82:83], v[166:167]
	global_load_dwordx4 v[164:167], v142, s[100:101] offset:1280
	s_waitcnt vmcnt(23)
	v_pk_add_f32 v[76:77], v[76:77], v[168:169]
	v_pk_add_f32 v[78:79], v[78:79], v[170:171]
	global_load_dwordx4 v[168:171], v142, s[100:101] offset:2304
	s_waitcnt vmcnt(23)
	v_pk_add_f32 v[72:73], v[72:73], v[172:173]
	v_pk_add_f32 v[74:75], v[74:75], v[174:175]
	global_load_dwordx4 v[172:175], v142, s[100:101] offset:3328
	s_waitcnt vmcnt(23)
	v_pk_add_f32 v[102:103], v[102:103], v[176:177]
	v_pk_add_f32 v[104:105], v[104:105], v[178:179]
	global_load_dwordx4 v[176:179], v143, s[100:101] offset:256
	s_add_u32 s100, s100, 0x20000
	s_addc_u32 s101, s101, 0
	s_waitcnt vmcnt(23)
	v_pk_add_f32 v[100:101], v[100:101], v[180:181]
	v_pk_add_f32 v[96:97], v[96:97], v[182:183]
	global_load_dwordx4 v[180:183], v141, s[100:101] offset:1280
	s_waitcnt vmcnt(23)
	v_pk_add_f32 v[94:95], v[94:95], v[184:185]
	v_pk_add_f32 v[92:93], v[92:93], v[186:187]
	global_load_dwordx4 v[184:187], v141, s[100:101] offset:2304
	s_waitcnt vmcnt(23)
	v_pk_add_f32 v[90:91], v[90:91], v[188:189]
	v_pk_add_f32 v[86:87], v[86:87], v[190:191]
	global_load_dwordx4 v[188:191], v141, s[100:101] offset:3328
	s_waitcnt vmcnt(23)
	v_pk_add_f32 v[88:89], v[88:89], v[192:193]
	v_pk_add_f32 v[84:85], v[84:85], v[194:195]
	global_load_dwordx4 v[192:195], v142, s[100:101] offset:256
	s_waitcnt vmcnt(23)
	v_pk_add_f32 v[80:81], v[80:81], v[196:197]
	v_pk_add_f32 v[82:83], v[82:83], v[198:199]
	global_load_dwordx4 v[196:199], v142, s[100:101] offset:1280
	s_waitcnt vmcnt(23)
	v_pk_add_f32 v[76:77], v[76:77], v[200:201]
	v_pk_add_f32 v[78:79], v[78:79], v[202:203]
	global_load_dwordx4 v[200:203], v142, s[100:101] offset:2304
	s_waitcnt vmcnt(23)
	v_pk_add_f32 v[72:73], v[72:73], v[204:205]
	v_pk_add_f32 v[74:75], v[74:75], v[206:207]
	global_load_dwordx4 v[204:207], v142, s[100:101] offset:3328
	s_waitcnt vmcnt(23)
	v_pk_add_f32 v[102:103], v[102:103], v[224:225]
	v_pk_add_f32 v[104:105], v[104:105], v[226:227]
	global_load_dwordx4 v[224:227], v143, s[100:101] offset:256
	s_add_u32 s100, s100, 0x20000
	s_addc_u32 s101, s101, 0
	s_waitcnt vmcnt(23)
	v_pk_add_f32 v[100:101], v[100:101], v[112:113]
	v_pk_add_f32 v[96:97], v[96:97], v[114:115]
	global_load_dwordx4 v[112:115], v141, s[100:101] offset:1280
	s_waitcnt vmcnt(23)
	v_pk_add_f32 v[94:95], v[94:95], v[116:117]
	v_pk_add_f32 v[92:93], v[92:93], v[118:119]
	global_load_dwordx4 v[116:119], v141, s[100:101] offset:2304
	s_waitcnt vmcnt(23)
	v_pk_add_f32 v[90:91], v[90:91], v[120:121]
	v_pk_add_f32 v[86:87], v[86:87], v[122:123]
	global_load_dwordx4 v[120:123], v141, s[100:101] offset:3328
	s_waitcnt vmcnt(23)
	v_pk_add_f32 v[88:89], v[88:89], v[124:125]
	v_pk_add_f32 v[84:85], v[84:85], v[126:127]
	global_load_dwordx4 v[124:127], v142, s[100:101] offset:256
	s_waitcnt vmcnt(23)
	v_pk_add_f32 v[80:81], v[80:81], v[128:129]
	v_pk_add_f32 v[82:83], v[82:83], v[130:131]
	global_load_dwordx4 v[128:131], v142, s[100:101] offset:1280
	s_waitcnt vmcnt(23)
	v_pk_add_f32 v[76:77], v[76:77], v[132:133]
	v_pk_add_f32 v[78:79], v[78:79], v[134:135]
	global_load_dwordx4 v[132:135], v142, s[100:101] offset:2304
	s_waitcnt vmcnt(23)
	v_pk_add_f32 v[72:73], v[72:73], v[136:137]
	v_pk_add_f32 v[74:75], v[74:75], v[138:139]
	global_load_dwordx4 v[136:139], v142, s[100:101] offset:3328
	s_waitcnt vmcnt(23)
	v_pk_add_f32 v[102:103], v[102:103], v[144:145]
	v_pk_add_f32 v[104:105], v[104:105], v[146:147]
	global_load_dwordx4 v[144:147], v143, s[100:101] offset:256
	s_add_u32 s100, s100, 0x20000
	s_addc_u32 s101, s101, 0
	s_waitcnt vmcnt(23)
	v_pk_add_f32 v[100:101], v[100:101], v[148:149]
	v_pk_add_f32 v[96:97], v[96:97], v[150:151]
	global_load_dwordx4 v[148:151], v141, s[100:101] offset:1280
	s_waitcnt vmcnt(23)
	v_pk_add_f32 v[94:95], v[94:95], v[152:153]
	v_pk_add_f32 v[92:93], v[92:93], v[154:155]
	global_load_dwordx4 v[152:155], v141, s[100:101] offset:2304
	s_waitcnt vmcnt(23)
	v_pk_add_f32 v[90:91], v[90:91], v[156:157]
	v_pk_add_f32 v[86:87], v[86:87], v[158:159]
	global_load_dwordx4 v[156:159], v141, s[100:101] offset:3328
	s_waitcnt vmcnt(23)
	v_pk_add_f32 v[88:89], v[88:89], v[160:161]
	v_pk_add_f32 v[84:85], v[84:85], v[162:163]
	global_load_dwordx4 v[160:163], v142, s[100:101] offset:256
	s_waitcnt vmcnt(23)
	v_pk_add_f32 v[80:81], v[80:81], v[164:165]
	v_pk_add_f32 v[82:83], v[82:83], v[166:167]
	global_load_dwordx4 v[164:167], v142, s[100:101] offset:1280
	s_waitcnt vmcnt(23)
	v_pk_add_f32 v[76:77], v[76:77], v[168:169]
	v_pk_add_f32 v[78:79], v[78:79], v[170:171]
	global_load_dwordx4 v[168:171], v142, s[100:101] offset:2304
	s_waitcnt vmcnt(23)
	v_pk_add_f32 v[72:73], v[72:73], v[172:173]
	v_pk_add_f32 v[74:75], v[74:75], v[174:175]
	global_load_dwordx4 v[172:175], v142, s[100:101] offset:3328
	s_waitcnt vmcnt(23)
; __device__ __forceinline__ void phase_resid(const Params& p, const float* g, bool first, bool last, int nsplit) {
;     ...
;         for (int sp = 0; sp < nsplit; ++sp) {
; #pragma unroll
;             for (int i = 0; i < 8; ++i) mv[i] += *(const f32x4*)(part + (size_t)(sp * 16 + gw) * DM + lane * 4 + 256 * i);
;         }
	v_pk_add_f32 v[102:103], v[102:103], v[176:177]
	v_pk_add_f32 v[104:105], v[104:105], v[178:179]
	global_load_dwordx4 v[176:179], v143, s[100:101] offset:256
	s_add_u32 s100, s100, 0x20000
	s_addc_u32 s101, s101, 0
	s_waitcnt vmcnt(23)
	v_pk_add_f32 v[100:101], v[100:101], v[180:181]
	v_pk_add_f32 v[96:97], v[96:97], v[182:183]
	global_load_dwordx4 v[180:183], v141, s[100:101] offset:1280
	s_waitcnt vmcnt(23)
	v_pk_add_f32 v[94:95], v[94:95], v[184:185]
	v_pk_add_f32 v[92:93], v[92:93], v[186:187]
	global_load_dwordx4 v[184:187], v141, s[100:101] offset:2304
	s_waitcnt vmcnt(23)
	v_pk_add_f32 v[90:91], v[90:91], v[188:189]
	v_pk_add_f32 v[86:87], v[86:87], v[190:191]
	global_load_dwordx4 v[188:191], v141, s[100:101] offset:3328
	s_waitcnt vmcnt(23)
	v_pk_add_f32 v[88:89], v[88:89], v[192:193]
	v_pk_add_f32 v[84:85], v[84:85], v[194:195]
	global_load_dwordx4 v[192:195], v142, s[100:101] offset:256
	s_waitcnt vmcnt(23)
	v_pk_add_f32 v[80:81], v[80:81], v[196:197]
	v_pk_add_f32 v[82:83], v[82:83], v[198:199]
	global_load_dwordx4 v[196:199], v142, s[100:101] offset:1280
	s_waitcnt vmcnt(23)
	v_pk_add_f32 v[76:77], v[76:77], v[200:201]
	v_pk_add_f32 v[78:79], v[78:79], v[202:203]
	global_load_dwordx4 v[200:203], v142, s[100:101] offset:2304
	s_waitcnt vmcnt(23)
	v_pk_add_f32 v[72:73], v[72:73], v[204:205]
	v_pk_add_f32 v[74:75], v[74:75], v[206:207]
	global_load_dwordx4 v[204:207], v142, s[100:101] offset:3328
	s_waitcnt vmcnt(23)
	v_pk_add_f32 v[102:103], v[102:103], v[224:225]
	v_pk_add_f32 v[104:105], v[104:105], v[226:227]
	global_load_dwordx4 v[224:227], v143, s[100:101] offset:256
	s_add_u32 s100, s100, 0x20000
	s_addc_u32 s101, s101, 0
	s_waitcnt vmcnt(23)
	v_pk_add_f32 v[100:101], v[100:101], v[112:113]
	v_pk_add_f32 v[96:97], v[96:97], v[114:115]
	global_load_dwordx4 v[112:115], v141, s[100:101] offset:1280
	s_waitcnt vmcnt(23)
	v_pk_add_f32 v[94:95], v[94:95], v[116:117]
	v_pk_add_f32 v[92:93], v[92:93], v[118:119]
	global_load_dwordx4 v[116:119], v141, s[100:101] offset:2304
	s_waitcnt vmcnt(23)
	v_pk_add_f32 v[90:91], v[90:91], v[120:121]
	v_pk_add_f32 v[86:87], v[86:87], v[122:123]
	global_load_dwordx4 v[120:123], v141, s[100:101] offset:3328
	s_waitcnt vmcnt(23)
	v_pk_add_f32 v[88:89], v[88:89], v[124:125]
	v_pk_add_f32 v[84:85], v[84:85], v[126:127]
	global_load_dwordx4 v[124:127], v142, s[100:101] offset:256
	s_waitcnt vmcnt(23)
	v_pk_add_f32 v[80:81], v[80:81], v[128:129]
	v_pk_add_f32 v[82:83], v[82:83], v[130:131]
	global_load_dwordx4 v[128:131], v142, s[100:101] offset:1280
	s_waitcnt vmcnt(23)
	v_pk_add_f32 v[76:77], v[76:77], v[132:133]
	v_pk_add_f32 v[78:79], v[78:79], v[134:135]
	global_load_dwordx4 v[132:135], v142, s[100:101] offset:2304
	s_waitcnt vmcnt(23)
	v_pk_add_f32 v[72:73], v[72:73], v[136:137]
	v_pk_add_f32 v[74:75], v[74:75], v[138:139]
	global_load_dwordx4 v[136:139], v142, s[100:101] offset:3328
	s_waitcnt vmcnt(23)
	v_pk_add_f32 v[102:103], v[102:103], v[144:145]
	v_pk_add_f32 v[104:105], v[104:105], v[146:147]
	global_load_dwordx4 v[144:147], v143, s[100:101] offset:256
	s_add_u32 s100, s100, 0x20000
	s_addc_u32 s101, s101, 0
	s_waitcnt vmcnt(23)
	v_pk_add_f32 v[100:101], v[100:101], v[148:149]
	v_pk_add_f32 v[96:97], v[96:97], v[150:151]
	global_load_dwordx4 v[148:151], v141, s[100:101] offset:1280
	s_waitcnt vmcnt(23)
	v_pk_add_f32 v[94:95], v[94:95], v[152:153]
	v_pk_add_f32 v[92:93], v[92:93], v[154:155]
	global_load_dwordx4 v[152:155], v141, s[100:101] offset:2304
	s_waitcnt vmcnt(23)
	v_pk_add_f32 v[90:91], v[90:91], v[156:157]
	v_pk_add_f32 v[86:87], v[86:87], v[158:159]
	global_load_dwordx4 v[156:159], v141, s[100:101] offset:3328
	s_waitcnt vmcnt(23)
	v_pk_add_f32 v[88:89], v[88:89], v[160:161]
	v_pk_add_f32 v[84:85], v[84:85], v[162:163]
	global_load_dwordx4 v[160:163], v142, s[100:101] offset:256
	s_waitcnt vmcnt(23)
	v_pk_add_f32 v[80:81], v[80:81], v[164:165]
	v_pk_add_f32 v[82:83], v[82:83], v[166:167]
	global_load_dwordx4 v[164:167], v142, s[100:101] offset:1280
	s_waitcnt vmcnt(23)
	v_pk_add_f32 v[76:77], v[76:77], v[168:169]
	v_pk_add_f32 v[78:79], v[78:79], v[170:171]
	global_load_dwordx4 v[168:171], v142, s[100:101] offset:2304
	s_waitcnt vmcnt(23)
	v_pk_add_f32 v[72:73], v[72:73], v[172:173]
	v_pk_add_f32 v[74:75], v[74:75], v[174:175]
	global_load_dwordx4 v[172:175], v142, s[100:101] offset:3328
	s_waitcnt vmcnt(23)
	v_pk_add_f32 v[102:103], v[102:103], v[176:177]
	v_pk_add_f32 v[104:105], v[104:105], v[178:179]
	global_load_dwordx4 v[176:179], v143, s[100:101] offset:256
	s_add_u32 s100, s100, 0x20000
	s_addc_u32 s101, s101, 0
	s_waitcnt vmcnt(23)
	v_pk_add_f32 v[100:101], v[100:101], v[180:181]
	v_pk_add_f32 v[96:97], v[96:97], v[182:183]
	global_load_dwordx4 v[180:183], v141, s[100:101] offset:1280
	s_waitcnt vmcnt(23)
	v_pk_add_f32 v[94:95], v[94:95], v[184:185]
	v_pk_add_f32 v[92:93], v[92:93], v[186:187]
	global_load_dwordx4 v[184:187], v141, s[100:101] offset:2304
	s_waitcnt vmcnt(23)
	v_pk_add_f32 v[90:91], v[90:91], v[188:189]
	v_pk_add_f32 v[86:87], v[86:87], v[190:191]
	global_load_dwordx4 v[188:191], v141, s[100:101] offset:3328
	s_waitcnt vmcnt(23)
	v_pk_add_f32 v[88:89], v[88:89], v[192:193]
	v_pk_add_f32 v[84:85], v[84:85], v[194:195]
	global_load_dwordx4 v[192:195], v142, s[100:101] offset:256
	s_waitcnt vmcnt(23)
	v_pk_add_f32 v[80:81], v[80:81], v[196:197]
	v_pk_add_f32 v[82:83], v[82:83], v[198:199]
	global_load_dwordx4 v[196:199], v142, s[100:101] offset:1280
	s_waitcnt vmcnt(23)
	v_pk_add_f32 v[76:77], v[76:77], v[200:201]
	v_pk_add_f32 v[78:79], v[78:79], v[202:203]
	global_load_dwordx4 v[200:203], v142, s[100:101] offset:2304
	s_waitcnt vmcnt(23)
; __device__ __forceinline__ void phase_resid(const Params& p, const float* g, bool first, bool last, int nsplit) {
;     ...
;         for (int sp = 0; sp < nsplit; ++sp) {
; #pragma unroll
;             for (int i = 0; i < 8; ++i) mv[i] += *(const f32x4*)(part + (size_t)(sp * 16 + gw) * DM + lane * 4 + 256 * i);
;         }
	v_pk_add_f32 v[72:73], v[72:73], v[204:205]
	v_pk_add_f32 v[74:75], v[74:75], v[206:207]
	global_load_dwordx4 v[204:207], v142, s[100:101] offset:3328
	s_waitcnt vmcnt(23)
	v_pk_add_f32 v[102:103], v[102:103], v[224:225]
	v_pk_add_f32 v[104:105], v[104:105], v[226:227]
	global_load_dwordx4 v[224:227], v143, s[100:101] offset:256
	s_add_u32 s100, s100, 0x20000
	s_addc_u32 s101, s101, 0
	s_waitcnt vmcnt(23)
	v_pk_add_f32 v[100:101], v[100:101], v[112:113]
	v_pk_add_f32 v[96:97], v[96:97], v[114:115]
	global_load_dwordx4 v[112:115], v141, s[100:101] offset:1280
	s_waitcnt vmcnt(23)
	v_pk_add_f32 v[94:95], v[94:95], v[116:117]
	v_pk_add_f32 v[92:93], v[92:93], v[118:119]
	global_load_dwordx4 v[116:119], v141, s[100:101] offset:2304
	s_waitcnt vmcnt(23)
	v_pk_add_f32 v[90:91], v[90:91], v[120:121]
	v_pk_add_f32 v[86:87], v[86:87], v[122:123]
	global_load_dwordx4 v[120:123], v141, s[100:101] offset:3328
	s_waitcnt vmcnt(23)
	v_pk_add_f32 v[88:89], v[88:89], v[124:125]
	v_pk_add_f32 v[84:85], v[84:85], v[126:127]
	global_load_dwordx4 v[124:127], v142, s[100:101] offset:256
	s_waitcnt vmcnt(23)
	v_pk_add_f32 v[80:81], v[80:81], v[128:129]
	v_pk_add_f32 v[82:83], v[82:83], v[130:131]
	global_load_dwordx4 v[128:131], v142, s[100:101] offset:1280
	s_waitcnt vmcnt(23)
	v_pk_add_f32 v[76:77], v[76:77], v[132:133]
	v_pk_add_f32 v[78:79], v[78:79], v[134:135]
	global_load_dwordx4 v[132:135], v142, s[100:101] offset:2304
	s_waitcnt vmcnt(23)
	v_pk_add_f32 v[72:73], v[72:73], v[136:137]
	v_pk_add_f32 v[74:75], v[74:75], v[138:139]
	global_load_dwordx4 v[136:139], v142, s[100:101] offset:3328
	s_waitcnt vmcnt(23)
	v_pk_add_f32 v[102:103], v[102:103], v[144:145]
	v_pk_add_f32 v[104:105], v[104:105], v[146:147]
	global_load_dwordx4 v[144:147], v143, s[100:101] offset:256
	s_waitcnt vmcnt(23)
	v_pk_add_f32 v[100:101], v[100:101], v[148:149]
	v_pk_add_f32 v[96:97], v[96:97], v[150:151]
	s_waitcnt vmcnt(22)
	v_pk_add_f32 v[94:95], v[94:95], v[152:153]
	v_pk_add_f32 v[92:93], v[92:93], v[154:155]
	s_waitcnt vmcnt(21)
	v_pk_add_f32 v[90:91], v[90:91], v[156:157]
	v_pk_add_f32 v[86:87], v[86:87], v[158:159]
	s_waitcnt vmcnt(20)
	v_pk_add_f32 v[88:89], v[88:89], v[160:161]
	v_pk_add_f32 v[84:85], v[84:85], v[162:163]
	s_waitcnt vmcnt(19)
	v_pk_add_f32 v[80:81], v[80:81], v[164:165]
	v_pk_add_f32 v[82:83], v[82:83], v[166:167]
	s_waitcnt vmcnt(18)
	v_pk_add_f32 v[76:77], v[76:77], v[168:169]
	v_pk_add_f32 v[78:79], v[78:79], v[170:171]
	s_waitcnt vmcnt(17)
	v_pk_add_f32 v[72:73], v[72:73], v[172:173]
	v_pk_add_f32 v[74:75], v[74:75], v[174:175]
	s_waitcnt vmcnt(16)
	v_pk_add_f32 v[102:103], v[102:103], v[176:177]
	v_pk_add_f32 v[104:105], v[104:105], v[178:179]
	s_waitcnt vmcnt(15)
	v_pk_add_f32 v[100:101], v[100:101], v[180:181]
	v_pk_add_f32 v[96:97], v[96:97], v[182:183]
	s_waitcnt vmcnt(14)
	v_pk_add_f32 v[94:95], v[94:95], v[184:185]
	v_pk_add_f32 v[92:93], v[92:93], v[186:187]
	s_waitcnt vmcnt(13)
	v_pk_add_f32 v[90:91], v[90:91], v[188:189]
	v_pk_add_f32 v[86:87], v[86:87], v[190:191]
	s_waitcnt vmcnt(12)
	v_pk_add_f32 v[88:89], v[88:89], v[192:193]
	v_pk_add_f32 v[84:85], v[84:85], v[194:195]
	s_waitcnt vmcnt(11)
	v_pk_add_f32 v[80:81], v[80:81], v[196:197]
	v_pk_add_f32 v[82:83], v[82:83], v[198:199]
	s_waitcnt vmcnt(10)
	v_pk_add_f32 v[76:77], v[76:77], v[200:201]
	v_pk_add_f32 v[78:79], v[78:79], v[202:203]
	s_waitcnt vmcnt(9)
	v_pk_add_f32 v[72:73], v[72:73], v[204:205]
	v_pk_add_f32 v[74:75], v[74:75], v[206:207]
	s_waitcnt vmcnt(8)
	v_pk_add_f32 v[102:103], v[102:103], v[224:225]
	v_pk_add_f32 v[104:105], v[104:105], v[226:227]
	s_waitcnt vmcnt(7)
	v_pk_add_f32 v[100:101], v[100:101], v[112:113]
	v_pk_add_f32 v[96:97], v[96:97], v[114:115]
	s_waitcnt vmcnt(6)
	v_pk_add_f32 v[94:95], v[94:95], v[116:117]
	v_pk_add_f32 v[92:93], v[92:93], v[118:119]
	s_waitcnt vmcnt(5)
	v_pk_add_f32 v[90:91], v[90:91], v[120:121]
	v_pk_add_f32 v[86:87], v[86:87], v[122:123]
	s_waitcnt vmcnt(4)
	v_pk_add_f32 v[88:89], v[88:89], v[124:125]
	v_pk_add_f32 v[84:85], v[84:85], v[126:127]
	s_waitcnt vmcnt(3)
	v_pk_add_f32 v[80:81], v[80:81], v[128:129]
	v_pk_add_f32 v[82:83], v[82:83], v[130:131]
	s_waitcnt vmcnt(2)
	v_pk_add_f32 v[76:77], v[76:77], v[132:133]
	v_pk_add_f32 v[78:79], v[78:79], v[134:135]
	s_waitcnt vmcnt(1)
	v_pk_add_f32 v[72:73], v[72:73], v[136:137]
	v_pk_add_f32 v[74:75], v[74:75], v[138:139]
	s_waitcnt vmcnt(0) lgkmcnt(0)
	v_pk_add_f32 v[102:103], v[102:103], v[144:145]
	v_pk_add_f32 v[104:105], v[104:105], v[146:147]
	s_mov_b32 s10, 0x200000
	v_mul_f32_e32 v67, v101, v101
	v_mul_f32_e32 v70, v95, v95
	v_fmac_f32_e32 v67, v100, v100
	v_fmac_f32_e32 v70, v94, v94
	v_fmac_f32_e32 v67, v96, v96
	v_fmac_f32_e32 v70, v92, v92
	v_fmac_f32_e32 v67, v97, v97
	v_fmac_f32_e32 v70, v93, v93
	v_add_f32_e32 v67, v67, v70
	v_mul_f32_e32 v70, v91, v91
	v_fmac_f32_e32 v70, v90, v90
	v_fmac_f32_e32 v70, v86, v86
	v_fmac_f32_e32 v70, v87, v87
	v_add_f32_e32 v67, v67, v70
	v_mul_f32_e32 v70, v89, v89
	v_fmac_f32_e32 v70, v88, v88
	v_fmac_f32_e32 v70, v84, v84
	v_fmac_f32_e32 v70, v85, v85
	v_mov_b32_e32 v106, v81
	v_mov_b32_e32 v107, v77
	v_add_f32_e32 v67, v67, v70
	v_mov_b32_e32 v70, v80
	v_mov_b32_e32 v71, v76
	v_pk_mul_f32 v[106:107], v[106:107], v[106:107]
	s_mov_b32 s3, 0x800000
	v_pk_fma_f32 v[70:71], v[70:71], v[70:71], v[106:107]
	v_mov_b32_e32 v106, v82
	v_mov_b32_e32 v107, v78
	v_pk_fma_f32 v[70:71], v[106:107], v[106:107], v[70:71]
	v_mov_b32_e32 v106, v83
	v_mov_b32_e32 v107, v79
	v_pk_fma_f32 v[70:71], v[106:107], v[106:107], v[70:71]
	v_mov_b32_e32 v106, v73
	v_add_f32_e32 v67, v67, v70
	v_mov_b32_e32 v107, v103
	v_add_f32_e32 v67, v67, v71
	v_mov_b32_e32 v70, v72
	v_mov_b32_e32 v71, v102
	v_pk_mul_f32 v[106:107], v[106:107], v[106:107]
	s_movk_i32 s2, 0x1000
	v_pk_fma_f32 v[70:71], v[70:71], v[70:71], v[106:107]
	v_mov_b32_e32 v106, v74
	v_mov_b32_e32 v107, v104
	v_pk_fma_f32 v[70:71], v[106:107], v[106:107], v[70:71]
	v_mov_b32_e32 v106, v75
	v_mov_b32_e32 v107, v105
	v_pk_fma_f32 v[70:71], v[106:107], v[106:107], v[70:71]
	v_lshlrev_b32_e32 v0, 1, v0
	v_add_f32_e32 v67, v67, v70
	v_and_b32_e32 v70, 64, v215
	v_add_f32_e32 v67, v67, v71
	v_add_u32_e32 v70, 64, v70
	v_xor_b32_e32 v71, 32, v215
	v_cmp_lt_i32_e32 vcc, v71, v70
	s_nop 1
	v_cndmask_b32_e32 v71, v215, v71, vcc
	v_lshlrev_b32_e32 v99, 2, v71
	ds_bpermute_b32 v71, v99, v67
	s_waitcnt lgkmcnt(0)
	v_add_f32_e32 v67, v67, v71
	v_xor_b32_e32 v71, 16, v215
	v_cmp_lt_i32_e32 vcc, v71, v70
	s_nop 1
	v_cndmask_b32_e32 v71, v215, v71, vcc
	v_lshlrev_b32_e32 v106, 2, v71
	ds_bpermute_b32 v71, v106, v67
	s_waitcnt lgkmcnt(0)
	v_add_f32_e32 v67, v67, v71
	v_xor_b32_e32 v71, 8, v215
	v_cmp_lt_i32_e32 vcc, v71, v70
	s_nop 1
	v_cndmask_b32_e32 v71, v215, v71, vcc
	v_lshlrev_b32_e32 v107, 2, v71
	ds_bpermute_b32 v71, v107, v67
	s_waitcnt lgkmcnt(0)
	v_add_f32_e32 v67, v67, v71
	v_xor_b32_e32 v71, 4, v215
	v_cmp_lt_i32_e32 vcc, v71, v70
	s_nop 1
	v_cndmask_b32_e32 v71, v215, v71, vcc
	v_lshlrev_b32_e32 v108, 2, v71
	ds_bpermute_b32 v71, v108, v67
	s_waitcnt lgkmcnt(0)
	v_add_f32_e32 v67, v67, v71
	v_xor_b32_e32 v71, 2, v215
	v_cmp_lt_i32_e32 vcc, v71, v70
	s_nop 1
	v_cndmask_b32_e32 v71, v215, v71, vcc
	v_lshlrev_b32_e32 v109, 2, v71
	ds_bpermute_b32 v71, v109, v67
	s_waitcnt lgkmcnt(0)
	v_add_f32_e32 v67, v67, v71
	v_xor_b32_e32 v71, 1, v215
	v_cmp_lt_i32_e32 vcc, v71, v70
	s_nop 1
	v_cndmask_b32_e32 v70, v215, v71, vcc
	v_lshlrev_b32_e32 v111, 2, v70
	ds_bpermute_b32 v70, v111, v67
	s_waitcnt lgkmcnt(0)
	v_add_f32_e32 v67, v67, v70
	v_fmamk_f32 v67, v67, 0x3a000000, v212
	v_mul_f32_e32 v70, 0x4b800000, v67
	v_cmp_gt_f32_e32 vcc, s3, v67
	s_nop 1
	v_cndmask_b32_e32 v67, v67, v70, vcc
	v_rsq_f32_e32 v67, v67
	s_nop 0
	v_mul_f32_e32 v70, 0x45800000, v67
	v_cndmask_b32_e32 v70, v67, v70, vcc
	v_pk_mul_f32 v[94:95], v[94:95], v[70:71] op_sel_hi:[1,0]
	v_pk_mul_f32 v[100:101], v[100:101], v[70:71] op_sel_hi:[1,0]
	v_pk_fma_f32 v[58:59], v[6:7], v[94:95], v[58:59]
	v_pk_mul_f32 v[96:97], v[96:97], v[70:71] op_sel_hi:[1,0]
	v_pk_mul_f32 v[92:93], v[92:93], v[70:71] op_sel_hi:[1,0]
	v_mul_f32_e32 v71, v59, v59
	v_pk_fma_f32 v[62:63], v[2:3], v[100:101], v[62:63]
	v_pk_fma_f32 v[60:61], v[8:9], v[92:93], v[60:61]
	v_fmac_f32_e32 v71, v58, v58
	v_mul_f32_e32 v67, v63, v63
	v_fmac_f32_e32 v71, v60, v60
	v_pk_fma_f32 v[64:65], v[4:5], v[96:97], v[64:65]
	v_fmac_f32_e32 v67, v62, v62
	v_fmac_f32_e32 v71, v61, v61
	v_fmac_f32_e32 v67, v64, v64
	v_pk_mul_f32 v[90:91], v[90:91], v[70:71] op_sel_hi:[1,0]
	v_fmac_f32_e32 v67, v65, v65
	v_pk_fma_f32 v[54:55], v[10:11], v[90:91], v[54:55]
	v_add_f32_e32 v67, v67, v71
	v_pk_mul_f32 v[86:87], v[86:87], v[70:71] op_sel_hi:[1,0]
	v_mul_f32_e32 v71, v55, v55
	v_pk_fma_f32 v[56:57], v[12:13], v[86:87], v[56:57]
	v_fmac_f32_e32 v71, v54, v54
	v_fmac_f32_e32 v71, v56, v56
	v_fmac_f32_e32 v71, v57, v57
	v_pk_mul_f32 v[86:87], v[88:89], v[70:71] op_sel_hi:[1,0]
	v_add_f32_e32 v67, v71, v67
	v_pk_fma_f32 v[50:51], v[14:15], v[86:87], v[50:51]
	v_pk_mul_f32 v[84:85], v[84:85], v[70:71] op_sel_hi:[1,0]
	v_mul_f32_e32 v71, v51, v51
	v_pk_fma_f32 v[52:53], v[16:17], v[84:85], v[52:53]
	v_fmac_f32_e32 v71, v50, v50
	v_fmac_f32_e32 v71, v52, v52
	v_fmac_f32_e32 v71, v53, v53
	v_pk_mul_f32 v[80:81], v[80:81], v[70:71] op_sel_hi:[1,0]
	v_pk_mul_f32 v[76:77], v[76:77], v[70:71] op_sel_hi:[1,0]
	v_pk_fma_f32 v[46:47], v[18:19], v[80:81], v[46:47]
	v_pk_mul_f32 v[78:79], v[78:79], v[70:71] op_sel_hi:[1,0]
	v_pk_fma_f32 v[42:43], v[22:23], v[76:77], v[42:43]
	v_pk_mul_f32 v[82:83], v[82:83], v[70:71] op_sel_hi:[1,0]
	v_pk_fma_f32 v[44:45], v[24:25], v[78:79], v[44:45]
	v_mov_b32_e32 v78, v43
	v_mov_b32_e32 v79, v47
	v_pk_fma_f32 v[48:49], v[20:21], v[82:83], v[48:49]
	v_mov_b32_e32 v76, v42
	v_mov_b32_e32 v77, v46
	v_pk_mul_f32 v[78:79], v[78:79], v[78:79]
	v_pk_mul_f32 v[72:73], v[72:73], v[70:71] op_sel_hi:[1,0]
	v_pk_fma_f32 v[76:77], v[76:77], v[76:77], v[78:79]
	v_mov_b32_e32 v78, v44
	v_mov_b32_e32 v79, v48
	v_pk_fma_f32 v[76:77], v[78:79], v[78:79], v[76:77]
	v_mov_b32_e32 v78, v45
	v_mov_b32_e32 v79, v49
	v_add_f32_e32 v67, v71, v67
	v_pk_fma_f32 v[76:77], v[78:79], v[78:79], v[76:77]
	v_pk_mul_f32 v[74:75], v[74:75], v[70:71] op_sel_hi:[1,0]
	v_pk_fma_f32 v[38:39], v[26:27], v[72:73], v[38:39]
	v_pk_mul_f32 v[72:73], v[104:105], v[70:71] op_sel_hi:[1,0]
	v_pk_mul_f32 v[70:71], v[102:103], v[70:71] op_sel_hi:[1,0]
	v_add_f32_e32 v67, v77, v67
	v_pk_fma_f32 v[34:35], v[30:31], v[70:71], v[34:35]
	v_add_f32_e32 v67, v76, v67
	v_mov_b32_e32 v76, v35
	v_mov_b32_e32 v77, v39
	v_pk_fma_f32 v[40:41], v[28:29], v[74:75], v[40:41]
	v_pk_fma_f32 v[36:37], v[32:33], v[72:73], v[36:37]
	v_mov_b32_e32 v74, v34
	v_mov_b32_e32 v75, v38
	v_pk_mul_f32 v[76:77], v[76:77], v[76:77]
	v_mov_b32_e32 v72, v36
	v_mov_b32_e32 v73, v40
	v_pk_fma_f32 v[74:75], v[74:75], v[74:75], v[76:77]
	v_mov_b32_e32 v70, v37
	v_mov_b32_e32 v71, v41
	v_pk_fma_f32 v[72:73], v[72:73], v[72:73], v[74:75]
	s_nop 0
	v_pk_fma_f32 v[70:71], v[70:71], v[70:71], v[72:73]
	s_nop 0
	v_add_f32_e32 v67, v71, v67
	v_add_f32_e32 v67, v70, v67
	ds_bpermute_b32 v70, v99, v67
	v_mov_b32_e32 v99, v1
	v_lshl_add_u64 v[68:69], v[68:69], 0, v[98:99]
	global_store_dwordx4 v[68:69], v[62:65], off
	global_store_dwordx4 v[68:69], v[58:61], off offset:1024
	global_store_dwordx4 v[68:69], v[54:57], off offset:2048
	global_store_dwordx4 v[68:69], v[50:53], off offset:3072
	v_add_co_u32_e32 v68, vcc, s2, v68
	s_waitcnt lgkmcnt(0)
	v_add_f32_e32 v67, v67, v70
	ds_bpermute_b32 v70, v106, v67
	v_addc_co_u32_e32 v69, vcc, 0, v69, vcc
	global_store_dwordx4 v[68:69], v[46:49], off
	global_store_dwordx4 v[68:69], v[42:45], off offset:1024
	global_store_dwordx4 v[68:69], v[38:41], off offset:2048
	global_store_dwordx4 v[68:69], v[34:37], off offset:3072
	s_waitcnt lgkmcnt(0)
	v_add_f32_e32 v67, v67, v70
	ds_bpermute_b32 v70, v107, v67
	s_waitcnt lgkmcnt(0)
	v_add_f32_e32 v67, v67, v70
	ds_bpermute_b32 v70, v108, v67
	s_waitcnt lgkmcnt(0)
	v_add_f32_e32 v67, v67, v70
	ds_bpermute_b32 v70, v109, v67
	s_waitcnt lgkmcnt(0)
	v_add_f32_e32 v67, v67, v70
	ds_bpermute_b32 v70, v111, v67
	s_waitcnt lgkmcnt(0)
	v_add_f32_e32 v67, v67, v70
	v_fmamk_f32 v67, v67, 0x3a000000, v212
	v_mul_f32_e32 v70, 0x4b800000, v67
	v_cmp_gt_f32_e32 vcc, s3, v67
	s_mov_b64 s[2:3], 0x1cc00000
	s_nop 0
	v_cndmask_b32_e32 v67, v67, v70, vcc
	v_rsq_f32_e32 v67, v67
	s_nop 0
	v_mul_f32_e32 v68, 0x45800000, v67
	v_cndmask_b32_e32 v67, v67, v68, vcc
	v_lshl_add_u64 v[68:69], s[34:35], 0, v[0:1]
	v_lshlrev_b32_e32 v0, 1, v110
	v_lshl_add_u64 v[68:69], v[68:69], 0, v[0:1]
	v_lshl_add_u64 v[70:71], v[68:69], 0, s[2:3]
	v_mul_f32_e32 v0, v62, v67
	v_mul_f32_e32 v62, v63, v67
	s_mov_b32 s2, 0x1cc00000
	v_cvt_pk_bf16_f32 v62, v0, v62
	v_mul_f32_e32 v0, v64, v67
	v_mul_f32_e32 v63, v65, v67
	v_add_co_u32_e32 v64, vcc, s2, v68
	v_cvt_pk_bf16_f32 v63, v0, v63
	v_mul_f32_e32 v0, v58, v67
	s_nop 0
	v_addc_co_u32_e32 v65, vcc, 0, v69, vcc
	v_mul_f32_e32 v58, v59, v67
	global_store_dwordx2 v[64:65], v[62:63], off
	v_cvt_pk_bf16_f32 v58, v0, v58
	v_mul_f32_e32 v0, v60, v67
	v_mul_f32_e32 v59, v61, v67
	v_cvt_pk_bf16_f32 v59, v0, v59
	v_mul_f32_e32 v0, v54, v67
	v_mul_f32_e32 v54, v55, v67
	global_store_dwordx2 v[70:71], v[58:59], off offset:512
	v_cvt_pk_bf16_f32 v54, v0, v54
	v_mul_f32_e32 v0, v56, v67
	v_mul_f32_e32 v55, v57, v67
	v_cvt_pk_bf16_f32 v55, v0, v55
	v_mul_f32_e32 v0, v50, v67
	v_mul_f32_e32 v50, v51, v67
	global_store_dwordx2 v[70:71], v[54:55], off offset:1024
	v_cvt_pk_bf16_f32 v50, v0, v50
	v_mul_f32_e32 v0, v52, v67
	v_mul_f32_e32 v51, v53, v67
	v_cvt_pk_bf16_f32 v51, v0, v51
	v_mul_f32_e32 v0, v46, v67
	v_mul_f32_e32 v46, v47, v67
	global_store_dwordx2 v[70:71], v[50:51], off offset:1536
	v_cvt_pk_bf16_f32 v46, v0, v46
	v_mul_f32_e32 v0, v48, v67
	v_mul_f32_e32 v47, v49, v67
	v_cvt_pk_bf16_f32 v47, v0, v47
	v_mul_f32_e32 v0, v42, v67
	v_mul_f32_e32 v42, v43, v67
	global_store_dwordx2 v[70:71], v[46:47], off offset:2048
	v_cvt_pk_bf16_f32 v42, v0, v42
	v_mul_f32_e32 v0, v44, v67
	v_mul_f32_e32 v43, v45, v67
	v_cvt_pk_bf16_f32 v43, v0, v43
	v_mul_f32_e32 v0, v38, v67
	v_mul_f32_e32 v38, v39, v67
	global_store_dwordx2 v[70:71], v[42:43], off offset:2560
	v_cvt_pk_bf16_f32 v38, v0, v38
	v_mul_f32_e32 v0, v40, v67
	v_mul_f32_e32 v39, v41, v67
	v_cvt_pk_bf16_f32 v39, v0, v39
	v_mul_f32_e32 v0, v34, v67
	v_mul_f32_e32 v34, v35, v67
	v_mul_f32_e32 v35, v37, v67
	global_store_dwordx2 v[70:71], v[38:39], off offset:3072
	v_cvt_pk_bf16_f32 v34, v0, v34
	v_mul_f32_e32 v0, v36, v67
	v_cvt_pk_bf16_f32 v35, v0, v35
	global_store_dwordx2 v[70:71], v[34:35], off offset:3584
